# baseline (speedup 1.0000x reference)
; #define PG8_STAGE(bufoff, gbase, voff) do { _Pragma("unroll") for (int _i = 0; _i < 2; ++_i) \
;         __builtin_amdgcn_global_load_lds((const unsigned*)((const char*)(gbase) + (voff)[_i]), (LAS unsigned*)(lds + (bufoff) + ldsw + _i * 8192), 16, 0, 0); } while (0)
; #define PG8_LDA(dst, b, h) do { _Pragma("unroll") for (int m = 0; m < 4; ++m) _Pragma("unroll") for (int k = 0; k < 2; ++k) dst[m][k] = *(const LAS bf16x8*)(lds + PG8_SA(b, h) + aoff + m * 2048 + k * 1024); } while (0)
; #define PG8_LDB(dst, b, h) do { _Pragma("unroll") for (int n = 0; n < 2; ++n) _Pragma("unroll") for (int k = 0; k < 2; ++k) dst[n][k] = *(const LAS bf16x8*)(lds + PG8_SB(b, h) + boff + n * 2048 + k * 1024); } while (0)
; #define PG8_MMA(ai, bj, At, Bt) do { __builtin_amdgcn_s_setprio(1); _Pragma("unroll") for (int m = 0; m < 4; ++m) _Pragma("unroll") for (int n = 0; n < 2; ++n) _Pragma("unroll") for (int k = 0; k < 2; ++k) \
;         acc[ai][bj][m][n] = __builtin_amdgcn_mfma_f32_16x16x32_bf16(Bt[n][k], At[m][k], acc[ai][bj][m][n], 0, 0, 0); __builtin_amdgcn_s_setprio(0); } while (0)
; #define PG8_WAIT_V(n) asm volatile("s_waitcnt vmcnt(" #n ")" ::: "memory")
; template <class Epi, int N_, int K_, int LDA_>
; __device__ __forceinline__ void gemm_phase(LAS unsigned char* lds, const Gemm g, const Epi& E) {
;     ...
;         const bool has_next = S.next(ui + 1, nxt);
;         const char* nA = has_next ? (const char*)g.A + (size_t)nxt.pm * tstepA : cA; const char* nB = has_next ? (const char*)g.Bt + (size_t)nxt.pn * tstepB : cB;
;         for (int t = 0; t < nt; t += 2) {
;             const bool last = (t == nt - 2);
;             const char* a1 = cA + (size_t)(t + 1) * kstep;
;             const char* a2 = last ? nA : cA + (size_t)(t + 2) * kstep; const char* b2 = last ? nB : cB + (size_t)(t + 2) * kstep;
;             const char* a3 = a2 + kstep; const char* b3 = b2 + kstep;
;             PG8_LDB(B0, 0, 0); PG8_LDB(B1, 0, 1); PG8_SCHED; PG8_LDA(At, 0, 0); PG8_STAGE(PG8_SA(1, 1), a1 + hstepA, voffA);
;             PG8_WAIT_V(8); PG8_WAIT_L(0); PG8_BAR; PG8_MMA(0, 0, At, B0); PG8_MMA(0, 1, At, B1); PG8_BAR; PG8_SCHED;
;             PG8_LDA(At, 0, 1); PG8_STAGE(PG8_SB(0, 0), b2, voffB); PG8_STAGE(PG8_SB(0, 1), b2 + hstepB, voffB); PG8_STAGE(PG8_SA(0, 0), a2, voffA);
;             PG8_WAIT_V(8); PG8_WAIT_L(0); PG8_BAR; PG8_MMA(1, 0, At, B0); PG8_MMA(1, 1, At, B1); PG8_BAR; PG8_SCHED;
.LBB0_199:
	s_add_u32 s18, s16, 0xfffc0080
	s_addc_u32 s19, s17, -1
	s_add_i32 s40, 0, 0x10000
	s_cmp_eq_u32 s39, 12
	s_cselect_b32 s21, s11, s19
	s_cselect_b32 s20, s35, s18
	v_add_u32_e32 v138, s40, v140
	s_cselect_b32 s19, s9, s38
	s_cselect_b32 s18, s36, s37
	s_add_i32 s42, 0, 0x14000
	ds_read_b128 v[142:145], v138
	ds_read_b128 v[146:149], v138 offset:1024
	ds_read_b128 v[150:153], v138 offset:2048
	ds_read_b128 v[154:157], v138 offset:3072
	v_add_u32_e32 v138, s42, v140
	ds_read_b128 v[158:161], v138
	ds_read_b128 v[162:165], v138 offset:1024
	ds_read_b128 v[166:169], v138 offset:2048
	ds_read_b128 v[170:173], v138 offset:3072
	v_lshl_add_u64 v[138:139], s[16:17], 0, v[134:135]
	s_add_i32 m0, s23, 0xc000
	ds_read_b128 v[174:177], v141
	ds_read_b128 v[178:181], v141 offset:1024
	ds_read_b128 v[182:185], v141 offset:2048
	ds_read_b128 v[186:189], v141 offset:3072
	ds_read_b128 v[190:193], v141 offset:4096
	ds_read_b128 v[200:203], v141 offset:5120
	ds_read_b128 v[204:207], v141 offset:6144
	ds_read_b128 v[208:211], v141 offset:7168
	global_load_lds_dwordx4 v[138:139], off
	v_lshl_add_u64 v[138:139], s[16:17], 0, v[136:137]
	s_add_i32 m0, s23, 0xe000
	s_nop 0
	global_load_lds_dwordx4 v[138:139], off
	s_waitcnt vmcnt(8)
	s_waitcnt lgkmcnt(0)
	s_barrier
	s_setprio 1
	v_mfma_f32_16x16x32_bf16 v[124:127], v[142:145], v[174:177], v[124:127]
	v_mfma_f32_16x16x32_bf16 v[120:123], v[150:153], v[174:177], v[120:123]
	v_mfma_f32_16x16x32_bf16 v[108:111], v[142:145], v[182:185], v[108:111]
	v_mfma_f32_16x16x32_bf16 v[104:107], v[150:153], v[182:185], v[104:107]
	v_mfma_f32_16x16x32_bf16 v[92:95], v[142:145], v[190:193], v[92:95]
	v_mfma_f32_16x16x32_bf16 v[88:91], v[150:153], v[190:193], v[88:91]
	v_mfma_f32_16x16x32_bf16 v[76:79], v[142:145], v[204:207], v[76:79]
	v_mfma_f32_16x16x32_bf16 v[72:75], v[150:153], v[204:207], v[72:75]
	v_mfma_f32_16x16x32_bf16 v[124:127], v[146:149], v[178:181], v[124:127]
	v_mfma_f32_16x16x32_bf16 v[120:123], v[154:157], v[178:181], v[120:123]
	v_mfma_f32_16x16x32_bf16 v[108:111], v[146:149], v[186:189], v[108:111]
	v_mfma_f32_16x16x32_bf16 v[104:107], v[154:157], v[186:189], v[104:107]
	v_mfma_f32_16x16x32_bf16 v[92:95], v[146:149], v[200:203], v[92:95]
	v_mfma_f32_16x16x32_bf16 v[88:91], v[154:157], v[200:203], v[88:91]
	v_mfma_f32_16x16x32_bf16 v[76:79], v[146:149], v[208:211], v[76:79]
	v_mfma_f32_16x16x32_bf16 v[72:75], v[154:157], v[208:211], v[72:75]
	s_setprio 0
	s_setprio 1
	v_mfma_f32_16x16x32_bf16 v[116:119], v[158:161], v[174:177], v[116:119]
	v_mfma_f32_16x16x32_bf16 v[112:115], v[166:169], v[174:177], v[112:115]
	v_mfma_f32_16x16x32_bf16 v[100:103], v[158:161], v[182:185], v[100:103]
	v_mfma_f32_16x16x32_bf16 v[96:99], v[166:169], v[182:185], v[96:99]
	v_mfma_f32_16x16x32_bf16 v[84:87], v[158:161], v[190:193], v[84:87]
	v_mfma_f32_16x16x32_bf16 v[80:83], v[166:169], v[190:193], v[80:83]
	v_mfma_f32_16x16x32_bf16 v[68:71], v[158:161], v[204:207], v[68:71]
	v_mfma_f32_16x16x32_bf16 v[64:67], v[166:169], v[204:207], v[64:67]
	v_mfma_f32_16x16x32_bf16 v[116:119], v[162:165], v[178:181], v[116:119]
	v_mfma_f32_16x16x32_bf16 v[112:115], v[170:173], v[178:181], v[112:115]
	v_mfma_f32_16x16x32_bf16 v[100:103], v[162:165], v[186:189], v[100:103]
	v_mfma_f32_16x16x32_bf16 v[96:99], v[170:173], v[186:189], v[96:99]
	v_mfma_f32_16x16x32_bf16 v[84:87], v[162:165], v[200:203], v[84:87]
	v_mfma_f32_16x16x32_bf16 v[80:83], v[170:173], v[200:203], v[80:83]
	v_mfma_f32_16x16x32_bf16 v[68:71], v[162:165], v[208:211], v[68:71]
	v_mfma_f32_16x16x32_bf16 v[64:67], v[170:173], v[208:211], v[64:67]
	s_setprio 0
	s_barrier
	s_add_i32 s40, s40, s22
	v_lshl_add_u64 v[138:139], s[18:19], 0, v[196:197]
	s_mov_b32 m0, s40
	ds_read_b128 v[174:177], v141 offset:16384
	ds_read_b128 v[178:181], v141 offset:17408
	ds_read_b128 v[182:185], v141 offset:18432
	ds_read_b128 v[186:189], v141 offset:19456
	ds_read_b128 v[190:193], v141 offset:20480
	ds_read_b128 v[200:203], v141 offset:21504
	ds_read_b128 v[204:207], v141 offset:22528
	ds_read_b128 v[208:211], v141 offset:23552
	global_load_lds_dwordx4 v[138:139], off
	s_add_i32 m0, s40, 0x2000
	s_add_u32 s40, s18, 0x40000
	v_lshl_add_u64 v[194:195], s[18:19], 0, v[128:129]
	s_addc_u32 s41, s19, 0
	s_add_i32 s42, s42, s22
	global_load_lds_dwordx4 v[194:195], off
	v_lshl_add_u64 v[212:213], s[40:41], 0, v[196:197]
	s_mov_b32 m0, s42
	v_lshl_add_u64 v[214:215], s[20:21], 0, v[130:131]
	global_load_lds_dwordx4 v[212:213], off
	v_lshl_add_u64 v[212:213], s[40:41], 0, v[128:129]
	s_add_i32 m0, s42, 0x2000
	s_nop 0
	global_load_lds_dwordx4 v[212:213], off
	v_lshl_add_u64 v[212:213], s[20:21], 0, v[132:133]
	s_mov_b32 m0, s23
	s_nop 0
	global_load_lds_dwordx4 v[212:213], off
	s_mov_b32 m0, s24
	s_nop 0
	global_load_lds_dwordx4 v[214:215], off
	s_waitcnt vmcnt(8)
	s_waitcnt lgkmcnt(0)
	s_barrier
; #define PG8_STAGE(bufoff, gbase, voff) do { _Pragma("unroll") for (int _i = 0; _i < 2; ++_i) \
;         __builtin_amdgcn_global_load_lds((const unsigned*)((const char*)(gbase) + (voff)[_i]), (LAS unsigned*)(lds + (bufoff) + ldsw + _i * 8192), 16, 0, 0); } while (0)
; #define PG8_LDA(dst, b, h) do { _Pragma("unroll") for (int m = 0; m < 4; ++m) _Pragma("unroll") for (int k = 0; k < 2; ++k) dst[m][k] = *(const LAS bf16x8*)(lds + PG8_SA(b, h) + aoff + m * 2048 + k * 1024); } while (0)
; #define PG8_LDB(dst, b, h) do { _Pragma("unroll") for (int n = 0; n < 2; ++n) _Pragma("unroll") for (int k = 0; k < 2; ++k) dst[n][k] = *(const LAS bf16x8*)(lds + PG8_SB(b, h) + boff + n * 2048 + k * 1024); } while (0)
; #define PG8_MMA(ai, bj, At, Bt) do { __builtin_amdgcn_s_setprio(1); _Pragma("unroll") for (int m = 0; m < 4; ++m) _Pragma("unroll") for (int n = 0; n < 2; ++n) _Pragma("unroll") for (int k = 0; k < 2; ++k) \
;         acc[ai][bj][m][n] = __builtin_amdgcn_mfma_f32_16x16x32_bf16(Bt[n][k], At[m][k], acc[ai][bj][m][n], 0, 0, 0); __builtin_amdgcn_s_setprio(0); } while (0)
; #define PG8_WAIT_V(n) asm volatile("s_waitcnt vmcnt(" #n ")" ::: "memory")
; #define PG8_WAIT_L(n) asm volatile("s_waitcnt lgkmcnt(" #n ")" ::: "memory")
; #define PG8_BAR __builtin_amdgcn_s_barrier()
; #define PG8_SCHED __builtin_amdgcn_sched_barrier(0)
; template <class Epi, int N_, int K_, int LDA_>
; __device__ __forceinline__ void gemm_phase(LAS unsigned char* lds, const Gemm g, const Epi& E) {
;     ...
;             PG8_WAIT_V(8); PG8_WAIT_L(0); PG8_BAR; PG8_MMA(1, 0, At, B0); PG8_MMA(1, 1, At, B1); PG8_BAR; PG8_SCHED;
;             PG8_LDB(B0, 1, 0); PG8_LDB(B1, 1, 1); PG8_SCHED; PG8_LDA(At, 1, 0); PG8_STAGE(PG8_SA(0, 1), a2 + hstepA, voffA);
;             PG8_WAIT_V(8); PG8_WAIT_L(0); PG8_BAR; PG8_MMA(0, 0, At, B0); PG8_MMA(0, 1, At, B1); PG8_BAR; PG8_SCHED;
	s_setprio 1
	v_mfma_f32_16x16x32_bf16 v[60:63], v[142:145], v[174:177], v[60:63]
	v_mfma_f32_16x16x32_bf16 v[56:59], v[150:153], v[174:177], v[56:59]
	v_mfma_f32_16x16x32_bf16 v[44:47], v[142:145], v[182:185], v[44:47]
	v_mfma_f32_16x16x32_bf16 v[40:43], v[150:153], v[182:185], v[40:43]
	v_mfma_f32_16x16x32_bf16 v[28:31], v[142:145], v[190:193], v[28:31]
	v_mfma_f32_16x16x32_bf16 v[24:27], v[150:153], v[190:193], v[24:27]
	v_mfma_f32_16x16x32_bf16 v[12:15], v[142:145], v[204:207], v[12:15]
	v_mfma_f32_16x16x32_bf16 v[8:11], v[150:153], v[204:207], v[8:11]
	v_mfma_f32_16x16x32_bf16 v[60:63], v[146:149], v[178:181], v[60:63]
	v_mfma_f32_16x16x32_bf16 v[56:59], v[154:157], v[178:181], v[56:59]
	v_mfma_f32_16x16x32_bf16 v[44:47], v[146:149], v[186:189], v[44:47]
	v_mfma_f32_16x16x32_bf16 v[40:43], v[154:157], v[186:189], v[40:43]
	v_mfma_f32_16x16x32_bf16 v[28:31], v[146:149], v[200:203], v[28:31]
	v_mfma_f32_16x16x32_bf16 v[24:27], v[154:157], v[200:203], v[24:27]
	v_mfma_f32_16x16x32_bf16 v[12:15], v[146:149], v[208:211], v[12:15]
	v_mfma_f32_16x16x32_bf16 v[8:11], v[154:157], v[208:211], v[8:11]
	s_setprio 0
	s_setprio 1
	v_mfma_f32_16x16x32_bf16 v[52:55], v[158:161], v[174:177], v[52:55]
	v_mfma_f32_16x16x32_bf16 v[48:51], v[166:169], v[174:177], v[48:51]
	v_mfma_f32_16x16x32_bf16 v[36:39], v[158:161], v[182:185], v[36:39]
	v_mfma_f32_16x16x32_bf16 v[32:35], v[166:169], v[182:185], v[32:35]
	v_mfma_f32_16x16x32_bf16 v[20:23], v[158:161], v[190:193], v[20:23]
	v_mfma_f32_16x16x32_bf16 v[16:19], v[166:169], v[190:193], v[16:19]
	v_mfma_f32_16x16x32_bf16 v[4:7], v[158:161], v[204:207], v[4:7]
	v_mfma_f32_16x16x32_bf16 v[0:3], v[166:169], v[204:207], v[0:3]
	v_mfma_f32_16x16x32_bf16 v[52:55], v[162:165], v[178:181], v[52:55]
	v_mfma_f32_16x16x32_bf16 v[48:51], v[170:173], v[178:181], v[48:51]
	v_mfma_f32_16x16x32_bf16 v[36:39], v[162:165], v[186:189], v[36:39]
	v_mfma_f32_16x16x32_bf16 v[32:35], v[170:173], v[186:189], v[32:35]
	v_mfma_f32_16x16x32_bf16 v[20:23], v[162:165], v[200:203], v[20:23]
	v_mfma_f32_16x16x32_bf16 v[16:19], v[170:173], v[200:203], v[16:19]
	v_mfma_f32_16x16x32_bf16 v[4:7], v[162:165], v[208:211], v[4:7]
	v_mfma_f32_16x16x32_bf16 v[0:3], v[170:173], v[208:211], v[0:3]
	s_setprio 0
	s_barrier
	s_add_i32 s40, 0, 0x18000
	s_add_i32 s41, 0, 0x1c000
	v_add_u32_e32 v154, s40, v140
	v_add_u32_e32 v170, s41, v140
	ds_read_b128 v[142:145], v154
	ds_read_b128 v[146:149], v154 offset:1024
	ds_read_b128 v[150:153], v154 offset:2048
	ds_read_b128 v[154:157], v154 offset:3072
	ds_read_b128 v[158:161], v170
	ds_read_b128 v[162:165], v170 offset:1024
	ds_read_b128 v[166:169], v170 offset:2048
	ds_read_b128 v[170:173], v170 offset:3072
	s_add_u32 s20, s20, 0x40000
	s_addc_u32 s21, s21, 0
	s_mov_b32 m0, s25
	v_lshl_add_u64 v[216:217], s[20:21], 0, v[132:133]
	ds_read_b128 v[174:177], v141 offset:32768
	ds_read_b128 v[178:181], v141 offset:33792
	ds_read_b128 v[182:185], v141 offset:34816
	ds_read_b128 v[186:189], v141 offset:35840
	ds_read_b128 v[190:193], v141 offset:36864
	ds_read_b128 v[200:203], v141 offset:37888
	ds_read_b128 v[204:207], v141 offset:38912
	ds_read_b128 v[208:211], v141 offset:39936
	global_load_lds_dwordx4 v[216:217], off
	v_lshl_add_u64 v[216:217], s[20:21], 0, v[130:131]
	s_mov_b32 m0, s26
	s_nop 0
	global_load_lds_dwordx4 v[216:217], off
	s_waitcnt vmcnt(8)
	s_waitcnt lgkmcnt(0)
	s_barrier
	s_setprio 1
	v_mfma_f32_16x16x32_bf16 v[124:127], v[142:145], v[174:177], v[124:127]
	v_mfma_f32_16x16x32_bf16 v[120:123], v[150:153], v[174:177], v[120:123]
	v_mfma_f32_16x16x32_bf16 v[108:111], v[142:145], v[182:185], v[108:111]
	v_mfma_f32_16x16x32_bf16 v[104:107], v[150:153], v[182:185], v[104:107]
	v_mfma_f32_16x16x32_bf16 v[92:95], v[142:145], v[190:193], v[92:95]
	v_mfma_f32_16x16x32_bf16 v[88:91], v[150:153], v[190:193], v[88:91]
	v_mfma_f32_16x16x32_bf16 v[76:79], v[142:145], v[204:207], v[76:79]
	v_mfma_f32_16x16x32_bf16 v[72:75], v[150:153], v[204:207], v[72:75]
	v_mfma_f32_16x16x32_bf16 v[124:127], v[146:149], v[178:181], v[124:127]
	v_mfma_f32_16x16x32_bf16 v[120:123], v[154:157], v[178:181], v[120:123]
	v_mfma_f32_16x16x32_bf16 v[108:111], v[146:149], v[186:189], v[108:111]
	v_mfma_f32_16x16x32_bf16 v[104:107], v[154:157], v[186:189], v[104:107]
	v_mfma_f32_16x16x32_bf16 v[92:95], v[146:149], v[200:203], v[92:95]
	v_mfma_f32_16x16x32_bf16 v[88:91], v[154:157], v[200:203], v[88:91]
	v_mfma_f32_16x16x32_bf16 v[76:79], v[146:149], v[208:211], v[76:79]
	v_mfma_f32_16x16x32_bf16 v[72:75], v[154:157], v[208:211], v[72:75]
	s_setprio 0
	s_setprio 1
	v_mfma_f32_16x16x32_bf16 v[116:119], v[158:161], v[174:177], v[116:119]
	v_mfma_f32_16x16x32_bf16 v[112:115], v[166:169], v[174:177], v[112:115]
	v_mfma_f32_16x16x32_bf16 v[100:103], v[158:161], v[182:185], v[100:103]
	v_mfma_f32_16x16x32_bf16 v[96:99], v[166:169], v[182:185], v[96:99]
	v_mfma_f32_16x16x32_bf16 v[84:87], v[158:161], v[190:193], v[84:87]
	v_mfma_f32_16x16x32_bf16 v[80:83], v[166:169], v[190:193], v[80:83]
	v_mfma_f32_16x16x32_bf16 v[68:71], v[158:161], v[204:207], v[68:71]
	v_mfma_f32_16x16x32_bf16 v[64:67], v[166:169], v[204:207], v[64:67]
	v_mfma_f32_16x16x32_bf16 v[116:119], v[162:165], v[178:181], v[116:119]
	v_mfma_f32_16x16x32_bf16 v[112:115], v[170:173], v[178:181], v[112:115]
	v_mfma_f32_16x16x32_bf16 v[100:103], v[162:165], v[186:189], v[100:103]
	v_mfma_f32_16x16x32_bf16 v[96:99], v[170:173], v[186:189], v[96:99]
	v_mfma_f32_16x16x32_bf16 v[84:87], v[162:165], v[200:203], v[84:87]
	v_mfma_f32_16x16x32_bf16 v[80:83], v[170:173], v[200:203], v[80:83]
	v_mfma_f32_16x16x32_bf16 v[68:71], v[162:165], v[208:211], v[68:71]
	v_mfma_f32_16x16x32_bf16 v[64:67], v[170:173], v[208:211], v[64:67]
	s_setprio 0
	s_barrier
; #define PG8_STAGE(bufoff, gbase, voff) do { _Pragma("unroll") for (int _i = 0; _i < 2; ++_i) \
;         __builtin_amdgcn_global_load_lds((const unsigned*)((const char*)(gbase) + (voff)[_i]), (LAS unsigned*)(lds + (bufoff) + ldsw + _i * 8192), 16, 0, 0); } while (0)
; #define PG8_LDA(dst, b, h) do { _Pragma("unroll") for (int m = 0; m < 4; ++m) _Pragma("unroll") for (int k = 0; k < 2; ++k) dst[m][k] = *(const LAS bf16x8*)(lds + PG8_SA(b, h) + aoff + m * 2048 + k * 1024); } while (0)
; #define PG8_MMA(ai, bj, At, Bt) do { __builtin_amdgcn_s_setprio(1); _Pragma("unroll") for (int m = 0; m < 4; ++m) _Pragma("unroll") for (int n = 0; n < 2; ++n) _Pragma("unroll") for (int k = 0; k < 2; ++k) \
;         acc[ai][bj][m][n] = __builtin_amdgcn_mfma_f32_16x16x32_bf16(Bt[n][k], At[m][k], acc[ai][bj][m][n], 0, 0, 0); __builtin_amdgcn_s_setprio(0); } while (0)
; #define PG8_WAIT_V(n) asm volatile("s_waitcnt vmcnt(" #n ")" ::: "memory")
; #define PG8_WAIT_L(n) asm volatile("s_waitcnt lgkmcnt(" #n ")" ::: "memory")
; #define PG8_BAR __builtin_amdgcn_s_barrier()
; #define PG8_SCHED __builtin_amdgcn_sched_barrier(0)
; template <class Epi, int N_, int K_, int LDA_>
; __device__ __forceinline__ void gemm_phase(LAS unsigned char* lds, const Gemm g, const Epi& E) {
;     ...
;             PG8_LDA(At, 1, 1); PG8_STAGE(PG8_SB(1, 0), b3, voffB); PG8_STAGE(PG8_SB(1, 1), b3 + hstepB, voffB); PG8_STAGE(PG8_SA(1, 0), a3, voffA);
;             PG8_WAIT_V(8); PG8_WAIT_L(0); PG8_BAR; PG8_MMA(1, 0, At, B0); PG8_MMA(1, 1, At, B1); PG8_BAR; PG8_SCHED;
;         }
;         if (wr == 0) PG8_BAR;
	s_add_i32 s20, s40, s22
	v_lshl_add_u64 v[138:139], v[138:139], 0, s[56:57]
	s_mov_b32 m0, s20
	ds_read_b128 v[174:177], v141 offset:49152
	ds_read_b128 v[178:181], v141 offset:50176
	ds_read_b128 v[182:185], v141 offset:51200
	ds_read_b128 v[186:189], v141 offset:52224
	ds_read_b128 v[190:193], v141 offset:53248
	ds_read_b128 v[200:203], v141 offset:54272
	ds_read_b128 v[204:207], v141 offset:55296
	ds_read_b128 v[208:211], v141 offset:56320
	global_load_lds_dwordx4 v[138:139], off
	s_add_i32 m0, s20, 0x2000
	s_add_u32 s18, s18, 0x40080
	v_lshl_add_u64 v[138:139], v[194:195], 0, s[56:57]
	s_addc_u32 s19, s19, 0
	s_add_i32 s20, s41, s22
	global_load_lds_dwordx4 v[138:139], off
	v_lshl_add_u64 v[138:139], s[18:19], 0, v[196:197]
	s_mov_b32 m0, s20
	s_nop 0
	global_load_lds_dwordx4 v[138:139], off
	v_lshl_add_u64 v[138:139], s[18:19], 0, v[128:129]
	s_add_i32 m0, s20, 0x2000
	s_nop 0
	global_load_lds_dwordx4 v[138:139], off
	v_lshl_add_u64 v[138:139], v[212:213], 0, s[56:57]
	s_mov_b32 m0, s29
	s_nop 0
	global_load_lds_dwordx4 v[138:139], off
	v_lshl_add_u64 v[138:139], v[214:215], 0, s[56:57]
	s_mov_b32 m0, s30
	s_nop 0
	global_load_lds_dwordx4 v[138:139], off
	s_waitcnt vmcnt(8)
	s_waitcnt lgkmcnt(0)
	s_barrier
	s_setprio 1
	v_mfma_f32_16x16x32_bf16 v[60:63], v[142:145], v[174:177], v[60:63]
	v_mfma_f32_16x16x32_bf16 v[56:59], v[150:153], v[174:177], v[56:59]
	v_mfma_f32_16x16x32_bf16 v[44:47], v[142:145], v[182:185], v[44:47]
	v_mfma_f32_16x16x32_bf16 v[40:43], v[150:153], v[182:185], v[40:43]
	v_mfma_f32_16x16x32_bf16 v[28:31], v[142:145], v[190:193], v[28:31]
	v_mfma_f32_16x16x32_bf16 v[24:27], v[150:153], v[190:193], v[24:27]
	v_mfma_f32_16x16x32_bf16 v[12:15], v[142:145], v[204:207], v[12:15]
	v_mfma_f32_16x16x32_bf16 v[8:11], v[150:153], v[204:207], v[8:11]
	v_mfma_f32_16x16x32_bf16 v[60:63], v[146:149], v[178:181], v[60:63]
	v_mfma_f32_16x16x32_bf16 v[56:59], v[154:157], v[178:181], v[56:59]
	v_mfma_f32_16x16x32_bf16 v[44:47], v[146:149], v[186:189], v[44:47]
	v_mfma_f32_16x16x32_bf16 v[40:43], v[154:157], v[186:189], v[40:43]
	v_mfma_f32_16x16x32_bf16 v[28:31], v[146:149], v[200:203], v[28:31]
	v_mfma_f32_16x16x32_bf16 v[24:27], v[154:157], v[200:203], v[24:27]
	v_mfma_f32_16x16x32_bf16 v[12:15], v[146:149], v[208:211], v[12:15]
	v_mfma_f32_16x16x32_bf16 v[8:11], v[154:157], v[208:211], v[8:11]
	s_setprio 0
	s_setprio 1
	v_mfma_f32_16x16x32_bf16 v[52:55], v[158:161], v[174:177], v[52:55]
	v_mfma_f32_16x16x32_bf16 v[48:51], v[166:169], v[174:177], v[48:51]
	v_mfma_f32_16x16x32_bf16 v[36:39], v[158:161], v[182:185], v[36:39]
	v_mfma_f32_16x16x32_bf16 v[32:35], v[166:169], v[182:185], v[32:35]
	v_mfma_f32_16x16x32_bf16 v[20:23], v[158:161], v[190:193], v[20:23]
	v_mfma_f32_16x16x32_bf16 v[16:19], v[166:169], v[190:193], v[16:19]
	v_mfma_f32_16x16x32_bf16 v[4:7], v[158:161], v[204:207], v[4:7]
	v_mfma_f32_16x16x32_bf16 v[0:3], v[166:169], v[204:207], v[0:3]
	v_mfma_f32_16x16x32_bf16 v[52:55], v[162:165], v[178:181], v[52:55]
	v_mfma_f32_16x16x32_bf16 v[48:51], v[170:173], v[178:181], v[48:51]
	v_mfma_f32_16x16x32_bf16 v[36:39], v[162:165], v[186:189], v[36:39]
	v_mfma_f32_16x16x32_bf16 v[32:35], v[170:173], v[186:189], v[32:35]
	v_mfma_f32_16x16x32_bf16 v[20:23], v[162:165], v[200:203], v[20:23]
	v_mfma_f32_16x16x32_bf16 v[16:19], v[170:173], v[200:203], v[16:19]
	v_mfma_f32_16x16x32_bf16 v[4:7], v[162:165], v[208:211], v[4:7]
	v_mfma_f32_16x16x32_bf16 v[0:3], v[170:173], v[208:211], v[0:3]
	s_setprio 0
	s_barrier
	s_add_i32 s39, s39, 2
	s_add_u32 s16, s16, 0x100
	s_addc_u32 s17, s17, 0
	s_add_u32 s37, s37, 0x100
	s_addc_u32 s38, s38, 0
	s_cmp_gt_u32 s39, 13
	s_cbranch_scc0 .LBB0_199
	s_and_b64 vcc, exec, s[2:3]
	s_cbranch_vccz .LBB0_202
	s_barrier

; #define PG8_STAGE(bufoff, gbase, voff) do { _Pragma("unroll") for (int _i = 0; _i < 2; ++_i) \
;         __builtin_amdgcn_global_load_lds((const unsigned*)((const char*)(gbase) + (voff)[_i]), (LAS unsigned*)(lds + (bufoff) + ldsw + _i * 8192), 16, 0, 0); } while (0)
; #define PG8_LDA(dst, b, h) do { _Pragma("unroll") for (int m = 0; m < 4; ++m) _Pragma("unroll") for (int k = 0; k < 2; ++k) dst[m][k] = *(const LAS bf16x8*)(lds + PG8_SA(b, h) + aoff + m * 2048 + k * 1024); } while (0)
; #define PG8_LDB(dst, b, h) do { _Pragma("unroll") for (int n = 0; n < 2; ++n) _Pragma("unroll") for (int k = 0; k < 2; ++k) dst[n][k] = *(const LAS bf16x8*)(lds + PG8_SB(b, h) + boff + n * 2048 + k * 1024); } while (0)
; #define PG8_MMA(ai, bj, At, Bt) do { __builtin_amdgcn_s_setprio(1); _Pragma("unroll") for (int m = 0; m < 4; ++m) _Pragma("unroll") for (int n = 0; n < 2; ++n) _Pragma("unroll") for (int k = 0; k < 2; ++k) \
;         acc[ai][bj][m][n] = __builtin_amdgcn_mfma_f32_16x16x32_bf16(Bt[n][k], At[m][k], acc[ai][bj][m][n], 0, 0, 0); __builtin_amdgcn_s_setprio(0); } while (0)
; #define PG8_WAIT_V(n) asm volatile("s_waitcnt vmcnt(" #n ")" ::: "memory")
; #define PG8_WAIT_L(n) asm volatile("s_waitcnt lgkmcnt(" #n ")" ::: "memory")
; #define PG8_BAR __builtin_amdgcn_s_barrier()
; #define PG8_SCHED __builtin_amdgcn_sched_barrier(0)
; template <class Epi, int N_, int K_, int LDA_>
; __device__ __forceinline__ void gemm_phase(LAS unsigned char* lds, const Gemm g, const Epi& E) {
;     ...
;         for (int t = 0; t < nt; t += 2) {
;             const bool last = (t == nt - 2);
;             const char* a1 = cA + (size_t)(t + 1) * kstep;
;             const char* a2 = last ? nA : cA + (size_t)(t + 2) * kstep; const char* b2 = last ? nB : cB + (size_t)(t + 2) * kstep;
;             const char* a3 = a2 + kstep; const char* b3 = b2 + kstep;
;             PG8_LDB(B0, 0, 0); PG8_LDB(B1, 0, 1); PG8_SCHED; PG8_LDA(At, 0, 0); PG8_STAGE(PG8_SA(1, 1), a1 + hstepA, voffA);
;             PG8_WAIT_V(8); PG8_WAIT_L(0); PG8_BAR; PG8_MMA(0, 0, At, B0); PG8_MMA(0, 1, At, B1); PG8_BAR; PG8_SCHED;
;             PG8_LDA(At, 0, 1); PG8_STAGE(PG8_SB(0, 0), b2, voffB); PG8_STAGE(PG8_SB(0, 1), b2 + hstepB, voffB); PG8_STAGE(PG8_SA(0, 0), a2, voffA);
.LBB0_277:
	s_add_u32 s0, s8, 0x100
	s_addc_u32 s1, s9, 0
	s_add_i32 s25, 0, 0x10000
	s_cmp_eq_u32 s24, 40
	s_cselect_b32 s23, s15, s1
	s_cselect_b32 s22, s14, s0
	s_cselect_b32 s11, s17, s21
	s_cselect_b32 s10, s16, s19
	s_add_i32 s44, 0, 0x14000
	v_add_u32_e32 v132, s25, v212
	v_add_u32_e32 v156, s44, v212
	ds_read_b128 v[112:115], v132
	ds_read_b128 v[116:119], v132 offset:1024
	ds_read_b128 v[124:127], v132 offset:2048
	ds_read_b128 v[132:135], v132 offset:3072
	ds_read_b128 v[144:147], v156
	ds_read_b128 v[148:151], v156 offset:1024
	ds_read_b128 v[152:155], v156 offset:2048
	ds_read_b128 v[156:159], v156 offset:3072
	v_lshl_add_u64 v[194:195], s[8:9], 0, v[182:183]
	s_add_i32 m0, s27, 0xc000
	ds_read_b128 v[160:163], v213
	ds_read_b128 v[164:167], v213 offset:1024
	ds_read_b128 v[168:171], v213 offset:2048
	ds_read_b128 v[172:175], v213 offset:3072
	ds_read_b128 v[186:189], v213 offset:4096
	ds_read_b128 v[190:193], v213 offset:5120
	ds_read_b128 v[200:203], v213 offset:6144
	ds_read_b128 v[204:207], v213 offset:7168
	global_load_lds_dwordx4 v[194:195], off
	v_lshl_add_u64 v[194:195], s[8:9], 0, v[184:185]
	s_add_i32 m0, s27, 0xe000
	s_nop 0
	global_load_lds_dwordx4 v[194:195], off
	s_waitcnt vmcnt(8)
	s_waitcnt lgkmcnt(0)
	s_barrier
	s_setprio 1
	v_mfma_f32_16x16x32_bf16 v[24:27], v[112:115], v[160:163], v[24:27]
	v_mfma_f32_16x16x32_bf16 v[28:31], v[124:127], v[160:163], v[28:31]
	v_mfma_f32_16x16x32_bf16 v[64:67], v[112:115], v[168:171], v[64:67]
	v_mfma_f32_16x16x32_bf16 v[68:71], v[124:127], v[168:171], v[68:71]
	v_mfma_f32_16x16x32_bf16 v[92:95], v[112:115], v[186:189], v[92:95]
	v_mfma_f32_16x16x32_bf16 v[88:91], v[124:127], v[186:189], v[88:91]
	v_mfma_f32_16x16x32_bf16 v[128:131], v[112:115], v[200:203], v[128:131]
	v_mfma_f32_16x16x32_bf16 v[120:123], v[124:127], v[200:203], v[120:123]
	v_mfma_f32_16x16x32_bf16 v[24:27], v[116:119], v[164:167], v[24:27]
	v_mfma_f32_16x16x32_bf16 v[28:31], v[132:135], v[164:167], v[28:31]
	v_mfma_f32_16x16x32_bf16 v[64:67], v[116:119], v[172:175], v[64:67]
	v_mfma_f32_16x16x32_bf16 v[68:71], v[132:135], v[172:175], v[68:71]
	v_mfma_f32_16x16x32_bf16 v[92:95], v[116:119], v[190:193], v[92:95]
	v_mfma_f32_16x16x32_bf16 v[88:91], v[132:135], v[190:193], v[88:91]
	v_mfma_f32_16x16x32_bf16 v[128:131], v[116:119], v[204:207], v[128:131]
	v_mfma_f32_16x16x32_bf16 v[120:123], v[132:135], v[204:207], v[120:123]
	s_setprio 0
	s_setprio 1
	v_mfma_f32_16x16x32_bf16 v[40:43], v[144:147], v[160:163], v[40:43]
	v_mfma_f32_16x16x32_bf16 v[44:47], v[152:155], v[160:163], v[44:47]
	v_mfma_f32_16x16x32_bf16 v[76:79], v[144:147], v[168:171], v[76:79]
	v_mfma_f32_16x16x32_bf16 v[72:75], v[152:155], v[168:171], v[72:75]
	v_mfma_f32_16x16x32_bf16 v[100:103], v[144:147], v[186:189], v[100:103]
	v_mfma_f32_16x16x32_bf16 v[96:99], v[152:155], v[186:189], v[96:99]
	v_mfma_f32_16x16x32_bf16 v[140:143], v[144:147], v[200:203], v[140:143]
	v_mfma_f32_16x16x32_bf16 v[136:139], v[152:155], v[200:203], v[136:139]
	v_mfma_f32_16x16x32_bf16 v[40:43], v[148:151], v[164:167], v[40:43]
	v_mfma_f32_16x16x32_bf16 v[44:47], v[156:159], v[164:167], v[44:47]
	v_mfma_f32_16x16x32_bf16 v[76:79], v[148:151], v[172:175], v[76:79]
	v_mfma_f32_16x16x32_bf16 v[72:75], v[156:159], v[172:175], v[72:75]
	v_mfma_f32_16x16x32_bf16 v[100:103], v[148:151], v[190:193], v[100:103]
	v_mfma_f32_16x16x32_bf16 v[96:99], v[156:159], v[190:193], v[96:99]
	v_mfma_f32_16x16x32_bf16 v[140:143], v[148:151], v[204:207], v[140:143]
	v_mfma_f32_16x16x32_bf16 v[136:139], v[156:159], v[204:207], v[136:139]
	s_setprio 0
	s_barrier
	s_add_i32 s8, s25, s26
	v_lshl_add_u64 v[194:195], s[10:11], 0, v[196:197]
	s_mov_b32 m0, s8
	ds_read_b128 v[160:163], v213 offset:16384
	ds_read_b128 v[164:167], v213 offset:17408
	ds_read_b128 v[168:171], v213 offset:18432
	ds_read_b128 v[172:175], v213 offset:19456
	ds_read_b128 v[186:189], v213 offset:20480
	ds_read_b128 v[190:193], v213 offset:21504
	ds_read_b128 v[200:203], v213 offset:22528
	ds_read_b128 v[204:207], v213 offset:23552
	global_load_lds_dwordx4 v[194:195], off
	s_add_i32 m0, s8, 0x2000
	s_add_u32 s8, s10, 0xb0000
	v_lshl_add_u64 v[208:209], s[10:11], 0, v[176:177]
	s_addc_u32 s9, s11, 0
	s_add_i32 s25, s44, s26
	global_load_lds_dwordx4 v[208:209], off
	v_lshl_add_u64 v[210:211], s[8:9], 0, v[196:197]
	s_mov_b32 m0, s25
	v_lshl_add_u64 v[214:215], s[22:23], 0, v[178:179]
	global_load_lds_dwordx4 v[210:211], off
	v_lshl_add_u64 v[210:211], s[8:9], 0, v[176:177]
	s_add_i32 m0, s25, 0x2000
	s_nop 0
	global_load_lds_dwordx4 v[210:211], off
	v_lshl_add_u64 v[210:211], s[22:23], 0, v[180:181]
	s_mov_b32 m0, s27
	s_nop 0
	global_load_lds_dwordx4 v[210:211], off
	s_mov_b32 m0, s28
	s_nop 0
	global_load_lds_dwordx4 v[214:215], off
	s_waitcnt vmcnt(8)
	s_waitcnt lgkmcnt(0)
	s_barrier
; #define PG8_STAGE(bufoff, gbase, voff) do { _Pragma("unroll") for (int _i = 0; _i < 2; ++_i) \
;         __builtin_amdgcn_global_load_lds((const unsigned*)((const char*)(gbase) + (voff)[_i]), (LAS unsigned*)(lds + (bufoff) + ldsw + _i * 8192), 16, 0, 0); } while (0)
; #define PG8_LDA(dst, b, h) do { _Pragma("unroll") for (int m = 0; m < 4; ++m) _Pragma("unroll") for (int k = 0; k < 2; ++k) dst[m][k] = *(const LAS bf16x8*)(lds + PG8_SA(b, h) + aoff + m * 2048 + k * 1024); } while (0)
; #define PG8_LDB(dst, b, h) do { _Pragma("unroll") for (int n = 0; n < 2; ++n) _Pragma("unroll") for (int k = 0; k < 2; ++k) dst[n][k] = *(const LAS bf16x8*)(lds + PG8_SB(b, h) + boff + n * 2048 + k * 1024); } while (0)
; #define PG8_MMA(ai, bj, At, Bt) do { __builtin_amdgcn_s_setprio(1); _Pragma("unroll") for (int m = 0; m < 4; ++m) _Pragma("unroll") for (int n = 0; n < 2; ++n) _Pragma("unroll") for (int k = 0; k < 2; ++k) \
;         acc[ai][bj][m][n] = __builtin_amdgcn_mfma_f32_16x16x32_bf16(Bt[n][k], At[m][k], acc[ai][bj][m][n], 0, 0, 0); __builtin_amdgcn_s_setprio(0); } while (0)
; #define PG8_WAIT_V(n) asm volatile("s_waitcnt vmcnt(" #n ")" ::: "memory")
; #define PG8_WAIT_L(n) asm volatile("s_waitcnt lgkmcnt(" #n ")" ::: "memory")
; #define PG8_BAR __builtin_amdgcn_s_barrier()
; #define PG8_SCHED __builtin_amdgcn_sched_barrier(0)
; template <class Epi, int N_, int K_, int LDA_>
; __device__ __forceinline__ void gemm_phase(LAS unsigned char* lds, const Gemm g, const Epi& E) {
;     ...
;             PG8_WAIT_V(8); PG8_WAIT_L(0); PG8_BAR; PG8_MMA(1, 0, At, B0); PG8_MMA(1, 1, At, B1); PG8_BAR; PG8_SCHED;
;             PG8_LDB(B0, 1, 0); PG8_LDB(B1, 1, 1); PG8_SCHED; PG8_LDA(At, 1, 0); PG8_STAGE(PG8_SA(0, 1), a2 + hstepA, voffA);
;             PG8_WAIT_V(8); PG8_WAIT_L(0); PG8_BAR; PG8_MMA(0, 0, At, B0); PG8_MMA(0, 1, At, B1); PG8_BAR; PG8_SCHED;
	s_setprio 1
	v_mfma_f32_16x16x32_bf16 v[108:111], v[112:115], v[160:163], v[108:111]
	v_mfma_f32_16x16x32_bf16 v[104:107], v[124:127], v[160:163], v[104:107]
	v_mfma_f32_16x16x32_bf16 v[60:63], v[112:115], v[168:171], v[60:63]
	v_mfma_f32_16x16x32_bf16 v[56:59], v[124:127], v[168:171], v[56:59]
	v_mfma_f32_16x16x32_bf16 v[36:39], v[112:115], v[186:189], v[36:39]
	v_mfma_f32_16x16x32_bf16 v[32:35], v[124:127], v[186:189], v[32:35]
	v_mfma_f32_16x16x32_bf16 v[12:15], v[112:115], v[200:203], v[12:15]
	v_mfma_f32_16x16x32_bf16 v[8:11], v[124:127], v[200:203], v[8:11]
	v_mfma_f32_16x16x32_bf16 v[108:111], v[116:119], v[164:167], v[108:111]
	v_mfma_f32_16x16x32_bf16 v[104:107], v[132:135], v[164:167], v[104:107]
	v_mfma_f32_16x16x32_bf16 v[60:63], v[116:119], v[172:175], v[60:63]
	v_mfma_f32_16x16x32_bf16 v[56:59], v[132:135], v[172:175], v[56:59]
	v_mfma_f32_16x16x32_bf16 v[36:39], v[116:119], v[190:193], v[36:39]
	v_mfma_f32_16x16x32_bf16 v[32:35], v[132:135], v[190:193], v[32:35]
	v_mfma_f32_16x16x32_bf16 v[12:15], v[116:119], v[204:207], v[12:15]
	v_mfma_f32_16x16x32_bf16 v[8:11], v[132:135], v[204:207], v[8:11]
	s_setprio 0
	s_setprio 1
	v_mfma_f32_16x16x32_bf16 v[84:87], v[144:147], v[160:163], v[84:87]
	v_mfma_f32_16x16x32_bf16 v[80:83], v[152:155], v[160:163], v[80:83]
	v_mfma_f32_16x16x32_bf16 v[52:55], v[144:147], v[168:171], v[52:55]
	v_mfma_f32_16x16x32_bf16 v[48:51], v[152:155], v[168:171], v[48:51]
	v_mfma_f32_16x16x32_bf16 v[20:23], v[144:147], v[186:189], v[20:23]
	v_mfma_f32_16x16x32_bf16 v[16:19], v[152:155], v[186:189], v[16:19]
	v_mfma_f32_16x16x32_bf16 v[4:7], v[144:147], v[200:203], v[4:7]
	v_mfma_f32_16x16x32_bf16 v[0:3], v[152:155], v[200:203], v[0:3]
	v_mfma_f32_16x16x32_bf16 v[84:87], v[148:151], v[164:167], v[84:87]
	v_mfma_f32_16x16x32_bf16 v[80:83], v[156:159], v[164:167], v[80:83]
	v_mfma_f32_16x16x32_bf16 v[52:55], v[148:151], v[172:175], v[52:55]
	v_mfma_f32_16x16x32_bf16 v[48:51], v[156:159], v[172:175], v[48:51]
	v_mfma_f32_16x16x32_bf16 v[20:23], v[148:151], v[190:193], v[20:23]
	v_mfma_f32_16x16x32_bf16 v[16:19], v[156:159], v[190:193], v[16:19]
	v_mfma_f32_16x16x32_bf16 v[4:7], v[148:151], v[204:207], v[4:7]
	v_mfma_f32_16x16x32_bf16 v[0:3], v[156:159], v[204:207], v[0:3]
	s_setprio 0
	s_barrier
	s_add_i32 s25, 0, 0x18000
	s_add_i32 s44, 0, 0x1c000
	v_add_u32_e32 v132, s25, v212
	v_add_u32_e32 v156, s44, v212
	ds_read_b128 v[112:115], v132
	ds_read_b128 v[116:119], v132 offset:1024
	ds_read_b128 v[124:127], v132 offset:2048
	ds_read_b128 v[132:135], v132 offset:3072
	ds_read_b128 v[144:147], v156
	ds_read_b128 v[148:151], v156 offset:1024
	ds_read_b128 v[152:155], v156 offset:2048
	ds_read_b128 v[156:159], v156 offset:3072
	s_add_u32 s8, s22, 0xb0000
	s_addc_u32 s9, s23, 0
	s_mov_b32 m0, s29
	v_lshl_add_u64 v[216:217], s[8:9], 0, v[180:181]
	ds_read_b128 v[160:163], v213 offset:32768
	ds_read_b128 v[164:167], v213 offset:33792
	ds_read_b128 v[168:171], v213 offset:34816
	ds_read_b128 v[172:175], v213 offset:35840
	ds_read_b128 v[186:189], v213 offset:36864
	ds_read_b128 v[190:193], v213 offset:37888
	ds_read_b128 v[200:203], v213 offset:38912
	ds_read_b128 v[204:207], v213 offset:39936
	global_load_lds_dwordx4 v[216:217], off
	v_lshl_add_u64 v[216:217], s[8:9], 0, v[178:179]
	s_mov_b32 m0, s30
	s_nop 0
	global_load_lds_dwordx4 v[216:217], off
	s_waitcnt vmcnt(8)
	s_waitcnt lgkmcnt(0)
	s_barrier
	s_setprio 1
	v_mfma_f32_16x16x32_bf16 v[24:27], v[112:115], v[160:163], v[24:27]
	v_mfma_f32_16x16x32_bf16 v[28:31], v[124:127], v[160:163], v[28:31]
	v_mfma_f32_16x16x32_bf16 v[64:67], v[112:115], v[168:171], v[64:67]
	v_mfma_f32_16x16x32_bf16 v[68:71], v[124:127], v[168:171], v[68:71]
	v_mfma_f32_16x16x32_bf16 v[92:95], v[112:115], v[186:189], v[92:95]
	v_mfma_f32_16x16x32_bf16 v[88:91], v[124:127], v[186:189], v[88:91]
	v_mfma_f32_16x16x32_bf16 v[128:131], v[112:115], v[200:203], v[128:131]
	v_mfma_f32_16x16x32_bf16 v[120:123], v[124:127], v[200:203], v[120:123]
	v_mfma_f32_16x16x32_bf16 v[24:27], v[116:119], v[164:167], v[24:27]
	v_mfma_f32_16x16x32_bf16 v[28:31], v[132:135], v[164:167], v[28:31]
	v_mfma_f32_16x16x32_bf16 v[64:67], v[116:119], v[172:175], v[64:67]
	v_mfma_f32_16x16x32_bf16 v[68:71], v[132:135], v[172:175], v[68:71]
	v_mfma_f32_16x16x32_bf16 v[92:95], v[116:119], v[190:193], v[92:95]
	v_mfma_f32_16x16x32_bf16 v[88:91], v[132:135], v[190:193], v[88:91]
	v_mfma_f32_16x16x32_bf16 v[128:131], v[116:119], v[204:207], v[128:131]
	v_mfma_f32_16x16x32_bf16 v[120:123], v[132:135], v[204:207], v[120:123]
	s_setprio 0
	s_setprio 1
	v_mfma_f32_16x16x32_bf16 v[40:43], v[144:147], v[160:163], v[40:43]
	v_mfma_f32_16x16x32_bf16 v[44:47], v[152:155], v[160:163], v[44:47]
	v_mfma_f32_16x16x32_bf16 v[76:79], v[144:147], v[168:171], v[76:79]
	v_mfma_f32_16x16x32_bf16 v[72:75], v[152:155], v[168:171], v[72:75]
	v_mfma_f32_16x16x32_bf16 v[100:103], v[144:147], v[186:189], v[100:103]
	v_mfma_f32_16x16x32_bf16 v[96:99], v[152:155], v[186:189], v[96:99]
	v_mfma_f32_16x16x32_bf16 v[140:143], v[144:147], v[200:203], v[140:143]
	v_mfma_f32_16x16x32_bf16 v[136:139], v[152:155], v[200:203], v[136:139]
	v_mfma_f32_16x16x32_bf16 v[40:43], v[148:151], v[164:167], v[40:43]
	v_mfma_f32_16x16x32_bf16 v[44:47], v[156:159], v[164:167], v[44:47]
	v_mfma_f32_16x16x32_bf16 v[76:79], v[148:151], v[172:175], v[76:79]
	v_mfma_f32_16x16x32_bf16 v[72:75], v[156:159], v[172:175], v[72:75]
	v_mfma_f32_16x16x32_bf16 v[100:103], v[148:151], v[190:193], v[100:103]
	v_mfma_f32_16x16x32_bf16 v[96:99], v[156:159], v[190:193], v[96:99]
	v_mfma_f32_16x16x32_bf16 v[140:143], v[148:151], v[204:207], v[140:143]
	v_mfma_f32_16x16x32_bf16 v[136:139], v[156:159], v[204:207], v[136:139]
	s_setprio 0
	s_barrier
; #define PG8_STAGE(bufoff, gbase, voff) do { _Pragma("unroll") for (int _i = 0; _i < 2; ++_i) \
;         __builtin_amdgcn_global_load_lds((const unsigned*)((const char*)(gbase) + (voff)[_i]), (LAS unsigned*)(lds + (bufoff) + ldsw + _i * 8192), 16, 0, 0); } while (0)
; #define PG8_LDA(dst, b, h) do { _Pragma("unroll") for (int m = 0; m < 4; ++m) _Pragma("unroll") for (int k = 0; k < 2; ++k) dst[m][k] = *(const LAS bf16x8*)(lds + PG8_SA(b, h) + aoff + m * 2048 + k * 1024); } while (0)
; #define PG8_MMA(ai, bj, At, Bt) do { __builtin_amdgcn_s_setprio(1); _Pragma("unroll") for (int m = 0; m < 4; ++m) _Pragma("unroll") for (int n = 0; n < 2; ++n) _Pragma("unroll") for (int k = 0; k < 2; ++k) \
;         acc[ai][bj][m][n] = __builtin_amdgcn_mfma_f32_16x16x32_bf16(Bt[n][k], At[m][k], acc[ai][bj][m][n], 0, 0, 0); __builtin_amdgcn_s_setprio(0); } while (0)
; #define PG8_WAIT_V(n) asm volatile("s_waitcnt vmcnt(" #n ")" ::: "memory")
; #define PG8_WAIT_L(n) asm volatile("s_waitcnt lgkmcnt(" #n ")" ::: "memory")
; #define PG8_BAR __builtin_amdgcn_s_barrier()
; #define PG8_SCHED __builtin_amdgcn_sched_barrier(0)
; template <class Epi, int N_, int K_, int LDA_>
; __device__ __forceinline__ void gemm_phase(LAS unsigned char* lds, const Gemm g, const Epi& E) {
;     ...
;             PG8_LDA(At, 1, 1); PG8_STAGE(PG8_SB(1, 0), b3, voffB); PG8_STAGE(PG8_SB(1, 1), b3 + hstepB, voffB); PG8_STAGE(PG8_SA(1, 0), a3, voffA);
;             PG8_WAIT_V(8); PG8_WAIT_L(0); PG8_BAR; PG8_MMA(1, 0, At, B0); PG8_MMA(1, 1, At, B1); PG8_BAR; PG8_SCHED;
;         }
;         if (wr == 0) PG8_BAR;
	s_add_i32 s8, s25, s26
	v_lshl_add_u64 v[194:195], v[194:195], 0, s[56:57]
	s_mov_b32 m0, s8
	ds_read_b128 v[160:163], v213 offset:49152
	ds_read_b128 v[164:167], v213 offset:50176
	ds_read_b128 v[168:171], v213 offset:51200
	ds_read_b128 v[172:175], v213 offset:52224
	ds_read_b128 v[186:189], v213 offset:53248
	ds_read_b128 v[190:193], v213 offset:54272
	ds_read_b128 v[200:203], v213 offset:55296
	ds_read_b128 v[204:207], v213 offset:56320
	global_load_lds_dwordx4 v[194:195], off
	s_add_i32 m0, s8, 0x2000
	s_add_u32 s8, s10, 0xb0080
	v_lshl_add_u64 v[194:195], v[208:209], 0, s[56:57]
	s_addc_u32 s9, s11, 0
	s_add_i32 s10, s44, s26
	global_load_lds_dwordx4 v[194:195], off
	v_lshl_add_u64 v[194:195], s[8:9], 0, v[196:197]
	s_mov_b32 m0, s10
	s_nop 0
	global_load_lds_dwordx4 v[194:195], off
	v_lshl_add_u64 v[194:195], s[8:9], 0, v[176:177]
	s_add_i32 m0, s10, 0x2000
	s_nop 0
	global_load_lds_dwordx4 v[194:195], off
	v_lshl_add_u64 v[194:195], v[210:211], 0, s[56:57]
	s_mov_b32 m0, s34
	s_nop 0
	global_load_lds_dwordx4 v[194:195], off
	v_lshl_add_u64 v[194:195], v[214:215], 0, s[56:57]
	s_mov_b32 m0, s35
	s_nop 0
	global_load_lds_dwordx4 v[194:195], off
	s_waitcnt vmcnt(8)
	s_waitcnt lgkmcnt(0)
	s_barrier
	s_setprio 1
	v_mfma_f32_16x16x32_bf16 v[108:111], v[112:115], v[160:163], v[108:111]
	v_mfma_f32_16x16x32_bf16 v[104:107], v[124:127], v[160:163], v[104:107]
	v_mfma_f32_16x16x32_bf16 v[60:63], v[112:115], v[168:171], v[60:63]
	v_mfma_f32_16x16x32_bf16 v[56:59], v[124:127], v[168:171], v[56:59]
	v_mfma_f32_16x16x32_bf16 v[36:39], v[112:115], v[186:189], v[36:39]
	v_mfma_f32_16x16x32_bf16 v[32:35], v[124:127], v[186:189], v[32:35]
	v_mfma_f32_16x16x32_bf16 v[12:15], v[112:115], v[200:203], v[12:15]
	v_mfma_f32_16x16x32_bf16 v[8:11], v[124:127], v[200:203], v[8:11]
	v_mfma_f32_16x16x32_bf16 v[108:111], v[116:119], v[164:167], v[108:111]
	v_mfma_f32_16x16x32_bf16 v[104:107], v[132:135], v[164:167], v[104:107]
	v_mfma_f32_16x16x32_bf16 v[60:63], v[116:119], v[172:175], v[60:63]
	v_mfma_f32_16x16x32_bf16 v[56:59], v[132:135], v[172:175], v[56:59]
	v_mfma_f32_16x16x32_bf16 v[36:39], v[116:119], v[190:193], v[36:39]
	v_mfma_f32_16x16x32_bf16 v[32:35], v[132:135], v[190:193], v[32:35]
	v_mfma_f32_16x16x32_bf16 v[12:15], v[116:119], v[204:207], v[12:15]
	v_mfma_f32_16x16x32_bf16 v[8:11], v[132:135], v[204:207], v[8:11]
	s_setprio 0
	s_setprio 1
	v_mfma_f32_16x16x32_bf16 v[84:87], v[144:147], v[160:163], v[84:87]
	v_mfma_f32_16x16x32_bf16 v[80:83], v[152:155], v[160:163], v[80:83]
	v_mfma_f32_16x16x32_bf16 v[52:55], v[144:147], v[168:171], v[52:55]
	v_mfma_f32_16x16x32_bf16 v[48:51], v[152:155], v[168:171], v[48:51]
	v_mfma_f32_16x16x32_bf16 v[20:23], v[144:147], v[186:189], v[20:23]
	v_mfma_f32_16x16x32_bf16 v[16:19], v[152:155], v[186:189], v[16:19]
	v_mfma_f32_16x16x32_bf16 v[4:7], v[144:147], v[200:203], v[4:7]
	v_mfma_f32_16x16x32_bf16 v[0:3], v[152:155], v[200:203], v[0:3]
	v_mfma_f32_16x16x32_bf16 v[84:87], v[148:151], v[164:167], v[84:87]
	v_mfma_f32_16x16x32_bf16 v[80:83], v[156:159], v[164:167], v[80:83]
	v_mfma_f32_16x16x32_bf16 v[52:55], v[148:151], v[172:175], v[52:55]
	v_mfma_f32_16x16x32_bf16 v[48:51], v[156:159], v[172:175], v[48:51]
	v_mfma_f32_16x16x32_bf16 v[20:23], v[148:151], v[190:193], v[20:23]
	v_mfma_f32_16x16x32_bf16 v[16:19], v[156:159], v[190:193], v[16:19]
	v_mfma_f32_16x16x32_bf16 v[4:7], v[148:151], v[204:207], v[4:7]
	v_mfma_f32_16x16x32_bf16 v[0:3], v[156:159], v[204:207], v[0:3]
	s_setprio 0
	s_barrier
	s_add_i32 s24, s24, 2
	s_add_u32 s19, s19, 0x100
	s_addc_u32 s21, s21, 0
	s_cmp_gt_u32 s24, 41
	s_mov_b64 s[8:9], s[0:1]
	s_cbranch_scc0 .LBB0_277
	s_and_b64 vcc, exec, s[12:13]
	s_cbranch_vccz .LBB0_280
	s_barrier

; #define PG8_STAGE(bufoff, gbase, voff) do { _Pragma("unroll") for (int _i = 0; _i < 2; ++_i) \
;         __builtin_amdgcn_global_load_lds((const unsigned*)((const char*)(gbase) + (voff)[_i]), (LAS unsigned*)(lds + (bufoff) + ldsw + _i * 8192), 16, 0, 0); } while (0)
; #define PG8_LDA(dst, b, h) do { _Pragma("unroll") for (int m = 0; m < 4; ++m) _Pragma("unroll") for (int k = 0; k < 2; ++k) dst[m][k] = *(const LAS bf16x8*)(lds + PG8_SA(b, h) + aoff + m * 2048 + k * 1024); } while (0)
; #define PG8_LDB(dst, b, h) do { _Pragma("unroll") for (int n = 0; n < 2; ++n) _Pragma("unroll") for (int k = 0; k < 2; ++k) dst[n][k] = *(const LAS bf16x8*)(lds + PG8_SB(b, h) + boff + n * 2048 + k * 1024); } while (0)
; #define PG8_MMA(ai, bj, At, Bt) do { __builtin_amdgcn_s_setprio(1); _Pragma("unroll") for (int m = 0; m < 4; ++m) _Pragma("unroll") for (int n = 0; n < 2; ++n) _Pragma("unroll") for (int k = 0; k < 2; ++k) \
;         acc[ai][bj][m][n] = __builtin_amdgcn_mfma_f32_16x16x32_bf16(Bt[n][k], At[m][k], acc[ai][bj][m][n], 0, 0, 0); __builtin_amdgcn_s_setprio(0); } while (0)
; #define PG8_WAIT_V(n) asm volatile("s_waitcnt vmcnt(" #n ")" ::: "memory")
; #define PG8_WAIT_L(n) asm volatile("s_waitcnt lgkmcnt(" #n ")" ::: "memory")
; #define PG8_BAR __builtin_amdgcn_s_barrier()
; #define PG8_SCHED __builtin_amdgcn_sched_barrier(0)
; template <class Epi, int N_, int K_, int LDA_>
; __device__ __forceinline__ void gemm_phase(LAS unsigned char* lds, const Gemm g, const Epi& E) {
;     ...
;         for (int t = 0; t < nt; t += 2) {
;             const bool last = (t == nt - 2);
;             const char* a1 = cA + (size_t)(t + 1) * kstep;
;             const char* a2 = last ? nA : cA + (size_t)(t + 2) * kstep; const char* b2 = last ? nB : cB + (size_t)(t + 2) * kstep;
;             const char* a3 = a2 + kstep; const char* b3 = b2 + kstep;
;             PG8_LDB(B0, 0, 0); PG8_LDB(B1, 0, 1); PG8_SCHED; PG8_LDA(At, 0, 0); PG8_STAGE(PG8_SA(1, 1), a1 + hstepA, voffA);
;             PG8_WAIT_V(8); PG8_WAIT_L(0); PG8_BAR; PG8_MMA(0, 0, At, B0); PG8_MMA(0, 1, At, B1); PG8_BAR; PG8_SCHED;
;             PG8_LDA(At, 0, 1); PG8_STAGE(PG8_SB(0, 0), b2, voffB); PG8_STAGE(PG8_SB(0, 1), b2 + hstepB, voffB); PG8_STAGE(PG8_SA(0, 0), a2, voffA);
.LBB0_349:
	s_add_u32 s16, s14, 0xfffc0080
	s_addc_u32 s17, s15, -1
	s_add_i32 s38, 0, 0x10000
	s_cmp_eq_u32 s37, 12
	s_cselect_b32 s19, s9, s17
	s_cselect_b32 s18, s33, s16
	s_cselect_b32 s17, s7, s36
	s_cselect_b32 s16, s34, s35
	s_add_i32 s40, 0, 0x14000
	v_add_u32_e32 v152, s38, v138
	v_add_u32_e32 v168, s40, v138
	ds_read_b128 v[140:143], v152
	ds_read_b128 v[144:147], v152 offset:1024
	ds_read_b128 v[148:151], v152 offset:2048
	ds_read_b128 v[152:155], v152 offset:3072
	ds_read_b128 v[156:159], v168
	ds_read_b128 v[160:163], v168 offset:1024
	ds_read_b128 v[164:167], v168 offset:2048
	ds_read_b128 v[168:171], v168 offset:3072
	v_lshl_add_u64 v[208:209], s[14:15], 0, v[134:135]
	s_add_i32 m0, s21, 0xc000
	ds_read_b128 v[172:175], v139
	ds_read_b128 v[176:179], v139 offset:1024
	ds_read_b128 v[180:183], v139 offset:2048
	ds_read_b128 v[184:187], v139 offset:3072
	ds_read_b128 v[188:191], v139 offset:4096
	ds_read_b128 v[192:195], v139 offset:5120
	ds_read_b128 v[200:203], v139 offset:6144
	ds_read_b128 v[204:207], v139 offset:7168
	global_load_lds_dwordx4 v[208:209], off
	v_lshl_add_u64 v[208:209], s[14:15], 0, v[136:137]
	s_add_i32 m0, s21, 0xe000
	s_nop 0
	global_load_lds_dwordx4 v[208:209], off
	s_waitcnt vmcnt(8)
	s_waitcnt lgkmcnt(0)
	s_barrier
	s_setprio 1
	v_mfma_f32_16x16x32_bf16 v[124:127], v[140:143], v[172:175], v[124:127]
	v_mfma_f32_16x16x32_bf16 v[120:123], v[148:151], v[172:175], v[120:123]
	v_mfma_f32_16x16x32_bf16 v[116:119], v[140:143], v[180:183], v[116:119]
	v_mfma_f32_16x16x32_bf16 v[112:115], v[148:151], v[180:183], v[112:115]
	v_mfma_f32_16x16x32_bf16 v[100:103], v[140:143], v[188:191], v[100:103]
	v_mfma_f32_16x16x32_bf16 v[96:99], v[148:151], v[188:191], v[96:99]
	v_mfma_f32_16x16x32_bf16 v[84:87], v[140:143], v[200:203], v[84:87]
	v_mfma_f32_16x16x32_bf16 v[80:83], v[148:151], v[200:203], v[80:83]
	v_mfma_f32_16x16x32_bf16 v[124:127], v[144:147], v[176:179], v[124:127]
	v_mfma_f32_16x16x32_bf16 v[120:123], v[152:155], v[176:179], v[120:123]
	v_mfma_f32_16x16x32_bf16 v[116:119], v[144:147], v[184:187], v[116:119]
	v_mfma_f32_16x16x32_bf16 v[112:115], v[152:155], v[184:187], v[112:115]
	v_mfma_f32_16x16x32_bf16 v[100:103], v[144:147], v[192:195], v[100:103]
	v_mfma_f32_16x16x32_bf16 v[96:99], v[152:155], v[192:195], v[96:99]
	v_mfma_f32_16x16x32_bf16 v[84:87], v[144:147], v[204:207], v[84:87]
	v_mfma_f32_16x16x32_bf16 v[80:83], v[152:155], v[204:207], v[80:83]
	s_setprio 0
	s_setprio 1
	v_mfma_f32_16x16x32_bf16 v[108:111], v[156:159], v[172:175], v[108:111]
	v_mfma_f32_16x16x32_bf16 v[104:107], v[164:167], v[172:175], v[104:107]
	v_mfma_f32_16x16x32_bf16 v[92:95], v[156:159], v[180:183], v[92:95]
	v_mfma_f32_16x16x32_bf16 v[88:91], v[164:167], v[180:183], v[88:91]
	v_mfma_f32_16x16x32_bf16 v[76:79], v[156:159], v[188:191], v[76:79]
	v_mfma_f32_16x16x32_bf16 v[72:75], v[164:167], v[188:191], v[72:75]
	v_mfma_f32_16x16x32_bf16 v[68:71], v[156:159], v[200:203], v[68:71]
	v_mfma_f32_16x16x32_bf16 v[64:67], v[164:167], v[200:203], v[64:67]
	v_mfma_f32_16x16x32_bf16 v[108:111], v[160:163], v[176:179], v[108:111]
	v_mfma_f32_16x16x32_bf16 v[104:107], v[168:171], v[176:179], v[104:107]
	v_mfma_f32_16x16x32_bf16 v[92:95], v[160:163], v[184:187], v[92:95]
	v_mfma_f32_16x16x32_bf16 v[88:91], v[168:171], v[184:187], v[88:91]
	v_mfma_f32_16x16x32_bf16 v[76:79], v[160:163], v[192:195], v[76:79]
	v_mfma_f32_16x16x32_bf16 v[72:75], v[168:171], v[192:195], v[72:75]
	v_mfma_f32_16x16x32_bf16 v[68:71], v[160:163], v[204:207], v[68:71]
	v_mfma_f32_16x16x32_bf16 v[64:67], v[168:171], v[204:207], v[64:67]
	s_setprio 0
	s_barrier
	s_add_i32 s38, s38, s20
	v_lshl_add_u64 v[208:209], s[16:17], 0, v[196:197]
	s_mov_b32 m0, s38
	ds_read_b128 v[172:175], v139 offset:16384
	ds_read_b128 v[176:179], v139 offset:17408
	ds_read_b128 v[180:183], v139 offset:18432
	ds_read_b128 v[184:187], v139 offset:19456
	ds_read_b128 v[188:191], v139 offset:20480
	ds_read_b128 v[192:195], v139 offset:21504
	ds_read_b128 v[200:203], v139 offset:22528
	ds_read_b128 v[204:207], v139 offset:23552
	global_load_lds_dwordx4 v[208:209], off
	s_add_i32 m0, s38, 0x2000
	s_add_u32 s38, s16, 0x40000
	v_lshl_add_u64 v[210:211], s[16:17], 0, v[128:129]
	s_addc_u32 s39, s17, 0
	s_add_i32 s40, s40, s20
	global_load_lds_dwordx4 v[210:211], off
	v_lshl_add_u64 v[212:213], s[38:39], 0, v[196:197]
	s_mov_b32 m0, s40
	v_lshl_add_u64 v[214:215], s[18:19], 0, v[130:131]
	global_load_lds_dwordx4 v[212:213], off
	v_lshl_add_u64 v[212:213], s[38:39], 0, v[128:129]
	s_add_i32 m0, s40, 0x2000
	s_nop 0
	global_load_lds_dwordx4 v[212:213], off
	v_lshl_add_u64 v[212:213], s[18:19], 0, v[132:133]
	s_mov_b32 m0, s21
	s_nop 0
	global_load_lds_dwordx4 v[212:213], off
	s_mov_b32 m0, s22
	s_nop 0
	global_load_lds_dwordx4 v[214:215], off
	s_waitcnt vmcnt(8)
	s_waitcnt lgkmcnt(0)
	s_barrier
; #define PG8_STAGE(bufoff, gbase, voff) do { _Pragma("unroll") for (int _i = 0; _i < 2; ++_i) \
;         __builtin_amdgcn_global_load_lds((const unsigned*)((const char*)(gbase) + (voff)[_i]), (LAS unsigned*)(lds + (bufoff) + ldsw + _i * 8192), 16, 0, 0); } while (0)
; #define PG8_LDA(dst, b, h) do { _Pragma("unroll") for (int m = 0; m < 4; ++m) _Pragma("unroll") for (int k = 0; k < 2; ++k) dst[m][k] = *(const LAS bf16x8*)(lds + PG8_SA(b, h) + aoff + m * 2048 + k * 1024); } while (0)
; #define PG8_LDB(dst, b, h) do { _Pragma("unroll") for (int n = 0; n < 2; ++n) _Pragma("unroll") for (int k = 0; k < 2; ++k) dst[n][k] = *(const LAS bf16x8*)(lds + PG8_SB(b, h) + boff + n * 2048 + k * 1024); } while (0)
; #define PG8_MMA(ai, bj, At, Bt) do { __builtin_amdgcn_s_setprio(1); _Pragma("unroll") for (int m = 0; m < 4; ++m) _Pragma("unroll") for (int n = 0; n < 2; ++n) _Pragma("unroll") for (int k = 0; k < 2; ++k) \
;         acc[ai][bj][m][n] = __builtin_amdgcn_mfma_f32_16x16x32_bf16(Bt[n][k], At[m][k], acc[ai][bj][m][n], 0, 0, 0); __builtin_amdgcn_s_setprio(0); } while (0)
; #define PG8_WAIT_V(n) asm volatile("s_waitcnt vmcnt(" #n ")" ::: "memory")
; #define PG8_WAIT_L(n) asm volatile("s_waitcnt lgkmcnt(" #n ")" ::: "memory")
; #define PG8_BAR __builtin_amdgcn_s_barrier()
; #define PG8_SCHED __builtin_amdgcn_sched_barrier(0)
; template <class Epi, int N_, int K_, int LDA_>
; __device__ __forceinline__ void gemm_phase(LAS unsigned char* lds, const Gemm g, const Epi& E) {
;     ...
;             PG8_WAIT_V(8); PG8_WAIT_L(0); PG8_BAR; PG8_MMA(1, 0, At, B0); PG8_MMA(1, 1, At, B1); PG8_BAR; PG8_SCHED;
;             PG8_LDB(B0, 1, 0); PG8_LDB(B1, 1, 1); PG8_SCHED; PG8_LDA(At, 1, 0); PG8_STAGE(PG8_SA(0, 1), a2 + hstepA, voffA);
;             PG8_WAIT_V(8); PG8_WAIT_L(0); PG8_BAR; PG8_MMA(0, 0, At, B0); PG8_MMA(0, 1, At, B1); PG8_BAR; PG8_SCHED;
	s_setprio 1
	v_mfma_f32_16x16x32_bf16 v[60:63], v[140:143], v[172:175], v[60:63]
	v_mfma_f32_16x16x32_bf16 v[56:59], v[148:151], v[172:175], v[56:59]
	v_mfma_f32_16x16x32_bf16 v[52:55], v[140:143], v[180:183], v[52:55]
	v_mfma_f32_16x16x32_bf16 v[48:51], v[148:151], v[180:183], v[48:51]
	v_mfma_f32_16x16x32_bf16 v[36:39], v[140:143], v[188:191], v[36:39]
	v_mfma_f32_16x16x32_bf16 v[32:35], v[148:151], v[188:191], v[32:35]
	v_mfma_f32_16x16x32_bf16 v[20:23], v[140:143], v[200:203], v[20:23]
	v_mfma_f32_16x16x32_bf16 v[16:19], v[148:151], v[200:203], v[16:19]
	v_mfma_f32_16x16x32_bf16 v[60:63], v[144:147], v[176:179], v[60:63]
	v_mfma_f32_16x16x32_bf16 v[56:59], v[152:155], v[176:179], v[56:59]
	v_mfma_f32_16x16x32_bf16 v[52:55], v[144:147], v[184:187], v[52:55]
	v_mfma_f32_16x16x32_bf16 v[48:51], v[152:155], v[184:187], v[48:51]
	v_mfma_f32_16x16x32_bf16 v[36:39], v[144:147], v[192:195], v[36:39]
	v_mfma_f32_16x16x32_bf16 v[32:35], v[152:155], v[192:195], v[32:35]
	v_mfma_f32_16x16x32_bf16 v[20:23], v[144:147], v[204:207], v[20:23]
	v_mfma_f32_16x16x32_bf16 v[16:19], v[152:155], v[204:207], v[16:19]
	s_setprio 0
	s_setprio 1
	v_mfma_f32_16x16x32_bf16 v[44:47], v[156:159], v[172:175], v[44:47]
	v_mfma_f32_16x16x32_bf16 v[40:43], v[164:167], v[172:175], v[40:43]
	v_mfma_f32_16x16x32_bf16 v[28:31], v[156:159], v[180:183], v[28:31]
	v_mfma_f32_16x16x32_bf16 v[24:27], v[164:167], v[180:183], v[24:27]
	v_mfma_f32_16x16x32_bf16 v[12:15], v[156:159], v[188:191], v[12:15]
	v_mfma_f32_16x16x32_bf16 v[8:11], v[164:167], v[188:191], v[8:11]
	v_mfma_f32_16x16x32_bf16 v[4:7], v[156:159], v[200:203], v[4:7]
	v_mfma_f32_16x16x32_bf16 v[0:3], v[164:167], v[200:203], v[0:3]
	v_mfma_f32_16x16x32_bf16 v[44:47], v[160:163], v[176:179], v[44:47]
	v_mfma_f32_16x16x32_bf16 v[40:43], v[168:171], v[176:179], v[40:43]
	v_mfma_f32_16x16x32_bf16 v[28:31], v[160:163], v[184:187], v[28:31]
	v_mfma_f32_16x16x32_bf16 v[24:27], v[168:171], v[184:187], v[24:27]
	v_mfma_f32_16x16x32_bf16 v[12:15], v[160:163], v[192:195], v[12:15]
	v_mfma_f32_16x16x32_bf16 v[8:11], v[168:171], v[192:195], v[8:11]
	v_mfma_f32_16x16x32_bf16 v[4:7], v[160:163], v[204:207], v[4:7]
	v_mfma_f32_16x16x32_bf16 v[0:3], v[168:171], v[204:207], v[0:3]
	s_setprio 0
	s_barrier
	s_add_i32 s38, 0, 0x18000
	s_add_i32 s39, 0, 0x1c000
	v_add_u32_e32 v152, s38, v138
	v_add_u32_e32 v168, s39, v138
	ds_read_b128 v[140:143], v152
	ds_read_b128 v[144:147], v152 offset:1024
	ds_read_b128 v[148:151], v152 offset:2048
	ds_read_b128 v[152:155], v152 offset:3072
	ds_read_b128 v[156:159], v168
	ds_read_b128 v[160:163], v168 offset:1024
	ds_read_b128 v[164:167], v168 offset:2048
	ds_read_b128 v[168:171], v168 offset:3072
	s_add_u32 s18, s18, 0x40000
	s_addc_u32 s19, s19, 0
	s_mov_b32 m0, s23
	v_lshl_add_u64 v[216:217], s[18:19], 0, v[132:133]
	ds_read_b128 v[172:175], v139 offset:32768
	ds_read_b128 v[176:179], v139 offset:33792
	ds_read_b128 v[180:183], v139 offset:34816
	ds_read_b128 v[184:187], v139 offset:35840
	ds_read_b128 v[188:191], v139 offset:36864
	ds_read_b128 v[192:195], v139 offset:37888
	ds_read_b128 v[200:203], v139 offset:38912
	ds_read_b128 v[204:207], v139 offset:39936
	global_load_lds_dwordx4 v[216:217], off
	v_lshl_add_u64 v[216:217], s[18:19], 0, v[130:131]
	s_mov_b32 m0, s24
	s_nop 0
	global_load_lds_dwordx4 v[216:217], off
	s_waitcnt vmcnt(8)
	s_waitcnt lgkmcnt(0)
	s_barrier
	s_setprio 1
	v_mfma_f32_16x16x32_bf16 v[124:127], v[140:143], v[172:175], v[124:127]
	v_mfma_f32_16x16x32_bf16 v[120:123], v[148:151], v[172:175], v[120:123]
	v_mfma_f32_16x16x32_bf16 v[116:119], v[140:143], v[180:183], v[116:119]
	v_mfma_f32_16x16x32_bf16 v[112:115], v[148:151], v[180:183], v[112:115]
	v_mfma_f32_16x16x32_bf16 v[100:103], v[140:143], v[188:191], v[100:103]
	v_mfma_f32_16x16x32_bf16 v[96:99], v[148:151], v[188:191], v[96:99]
	v_mfma_f32_16x16x32_bf16 v[84:87], v[140:143], v[200:203], v[84:87]
	v_mfma_f32_16x16x32_bf16 v[80:83], v[148:151], v[200:203], v[80:83]
	v_mfma_f32_16x16x32_bf16 v[124:127], v[144:147], v[176:179], v[124:127]
	v_mfma_f32_16x16x32_bf16 v[120:123], v[152:155], v[176:179], v[120:123]
	v_mfma_f32_16x16x32_bf16 v[116:119], v[144:147], v[184:187], v[116:119]
	v_mfma_f32_16x16x32_bf16 v[112:115], v[152:155], v[184:187], v[112:115]
	v_mfma_f32_16x16x32_bf16 v[100:103], v[144:147], v[192:195], v[100:103]
	v_mfma_f32_16x16x32_bf16 v[96:99], v[152:155], v[192:195], v[96:99]
	v_mfma_f32_16x16x32_bf16 v[84:87], v[144:147], v[204:207], v[84:87]
	v_mfma_f32_16x16x32_bf16 v[80:83], v[152:155], v[204:207], v[80:83]
	s_setprio 0
	s_setprio 1
	v_mfma_f32_16x16x32_bf16 v[108:111], v[156:159], v[172:175], v[108:111]
	v_mfma_f32_16x16x32_bf16 v[104:107], v[164:167], v[172:175], v[104:107]
	v_mfma_f32_16x16x32_bf16 v[92:95], v[156:159], v[180:183], v[92:95]
	v_mfma_f32_16x16x32_bf16 v[88:91], v[164:167], v[180:183], v[88:91]
	v_mfma_f32_16x16x32_bf16 v[76:79], v[156:159], v[188:191], v[76:79]
	v_mfma_f32_16x16x32_bf16 v[72:75], v[164:167], v[188:191], v[72:75]
	v_mfma_f32_16x16x32_bf16 v[68:71], v[156:159], v[200:203], v[68:71]
	v_mfma_f32_16x16x32_bf16 v[64:67], v[164:167], v[200:203], v[64:67]
	v_mfma_f32_16x16x32_bf16 v[108:111], v[160:163], v[176:179], v[108:111]
	v_mfma_f32_16x16x32_bf16 v[104:107], v[168:171], v[176:179], v[104:107]
	v_mfma_f32_16x16x32_bf16 v[92:95], v[160:163], v[184:187], v[92:95]
	v_mfma_f32_16x16x32_bf16 v[88:91], v[168:171], v[184:187], v[88:91]
	v_mfma_f32_16x16x32_bf16 v[76:79], v[160:163], v[192:195], v[76:79]
	v_mfma_f32_16x16x32_bf16 v[72:75], v[168:171], v[192:195], v[72:75]
	v_mfma_f32_16x16x32_bf16 v[68:71], v[160:163], v[204:207], v[68:71]
	v_mfma_f32_16x16x32_bf16 v[64:67], v[168:171], v[204:207], v[64:67]
	s_setprio 0
	s_barrier
; #define PG8_STAGE(bufoff, gbase, voff) do { _Pragma("unroll") for (int _i = 0; _i < 2; ++_i) \
;         __builtin_amdgcn_global_load_lds((const unsigned*)((const char*)(gbase) + (voff)[_i]), (LAS unsigned*)(lds + (bufoff) + ldsw + _i * 8192), 16, 0, 0); } while (0)
; #define PG8_LDA(dst, b, h) do { _Pragma("unroll") for (int m = 0; m < 4; ++m) _Pragma("unroll") for (int k = 0; k < 2; ++k) dst[m][k] = *(const LAS bf16x8*)(lds + PG8_SA(b, h) + aoff + m * 2048 + k * 1024); } while (0)
; #define PG8_MMA(ai, bj, At, Bt) do { __builtin_amdgcn_s_setprio(1); _Pragma("unroll") for (int m = 0; m < 4; ++m) _Pragma("unroll") for (int n = 0; n < 2; ++n) _Pragma("unroll") for (int k = 0; k < 2; ++k) \
;         acc[ai][bj][m][n] = __builtin_amdgcn_mfma_f32_16x16x32_bf16(Bt[n][k], At[m][k], acc[ai][bj][m][n], 0, 0, 0); __builtin_amdgcn_s_setprio(0); } while (0)
; #define PG8_WAIT_V(n) asm volatile("s_waitcnt vmcnt(" #n ")" ::: "memory")
; #define PG8_WAIT_L(n) asm volatile("s_waitcnt lgkmcnt(" #n ")" ::: "memory")
; #define PG8_BAR __builtin_amdgcn_s_barrier()
; #define PG8_SCHED __builtin_amdgcn_sched_barrier(0)
; template <class Epi, int N_, int K_, int LDA_>
; __device__ __forceinline__ void gemm_phase(LAS unsigned char* lds, const Gemm g, const Epi& E) {
;     ...
;             PG8_LDA(At, 1, 1); PG8_STAGE(PG8_SB(1, 0), b3, voffB); PG8_STAGE(PG8_SB(1, 1), b3 + hstepB, voffB); PG8_STAGE(PG8_SA(1, 0), a3, voffA);
;             PG8_WAIT_V(8); PG8_WAIT_L(0); PG8_BAR; PG8_MMA(1, 0, At, B0); PG8_MMA(1, 1, At, B1); PG8_BAR; PG8_SCHED;
;         }
;         if (wr == 0) PG8_BAR;
	s_add_i32 s18, s38, s20
	v_lshl_add_u64 v[208:209], v[208:209], 0, s[56:57]
	s_mov_b32 m0, s18
	ds_read_b128 v[172:175], v139 offset:49152
	ds_read_b128 v[176:179], v139 offset:50176
	ds_read_b128 v[180:183], v139 offset:51200
	ds_read_b128 v[184:187], v139 offset:52224
	ds_read_b128 v[188:191], v139 offset:53248
	ds_read_b128 v[192:195], v139 offset:54272
	ds_read_b128 v[200:203], v139 offset:55296
	ds_read_b128 v[204:207], v139 offset:56320
	global_load_lds_dwordx4 v[208:209], off
	s_add_i32 m0, s18, 0x2000
	s_add_u32 s16, s16, 0x40080
	v_lshl_add_u64 v[208:209], v[210:211], 0, s[56:57]
	s_addc_u32 s17, s17, 0
	s_add_i32 s18, s39, s20
	global_load_lds_dwordx4 v[208:209], off
	v_lshl_add_u64 v[208:209], s[16:17], 0, v[196:197]
	s_mov_b32 m0, s18
	s_nop 0
	global_load_lds_dwordx4 v[208:209], off
	v_lshl_add_u64 v[208:209], s[16:17], 0, v[128:129]
	s_add_i32 m0, s18, 0x2000
	s_nop 0
	global_load_lds_dwordx4 v[208:209], off
	v_lshl_add_u64 v[208:209], v[212:213], 0, s[56:57]
	s_mov_b32 m0, s27
	s_nop 0
	global_load_lds_dwordx4 v[208:209], off
	v_lshl_add_u64 v[208:209], v[214:215], 0, s[56:57]
	s_mov_b32 m0, s28
	s_nop 0
	global_load_lds_dwordx4 v[208:209], off
	s_waitcnt vmcnt(8)
	s_waitcnt lgkmcnt(0)
	s_barrier
	s_setprio 1
	v_mfma_f32_16x16x32_bf16 v[60:63], v[140:143], v[172:175], v[60:63]
	v_mfma_f32_16x16x32_bf16 v[56:59], v[148:151], v[172:175], v[56:59]
	v_mfma_f32_16x16x32_bf16 v[52:55], v[140:143], v[180:183], v[52:55]
	v_mfma_f32_16x16x32_bf16 v[48:51], v[148:151], v[180:183], v[48:51]
	v_mfma_f32_16x16x32_bf16 v[36:39], v[140:143], v[188:191], v[36:39]
	v_mfma_f32_16x16x32_bf16 v[32:35], v[148:151], v[188:191], v[32:35]
	v_mfma_f32_16x16x32_bf16 v[20:23], v[140:143], v[200:203], v[20:23]
	v_mfma_f32_16x16x32_bf16 v[16:19], v[148:151], v[200:203], v[16:19]
	v_mfma_f32_16x16x32_bf16 v[60:63], v[144:147], v[176:179], v[60:63]
	v_mfma_f32_16x16x32_bf16 v[56:59], v[152:155], v[176:179], v[56:59]
	v_mfma_f32_16x16x32_bf16 v[52:55], v[144:147], v[184:187], v[52:55]
	v_mfma_f32_16x16x32_bf16 v[48:51], v[152:155], v[184:187], v[48:51]
	v_mfma_f32_16x16x32_bf16 v[36:39], v[144:147], v[192:195], v[36:39]
	v_mfma_f32_16x16x32_bf16 v[32:35], v[152:155], v[192:195], v[32:35]
	v_mfma_f32_16x16x32_bf16 v[20:23], v[144:147], v[204:207], v[20:23]
	v_mfma_f32_16x16x32_bf16 v[16:19], v[152:155], v[204:207], v[16:19]
	s_setprio 0
	s_setprio 1
	v_mfma_f32_16x16x32_bf16 v[44:47], v[156:159], v[172:175], v[44:47]
	v_mfma_f32_16x16x32_bf16 v[40:43], v[164:167], v[172:175], v[40:43]
	v_mfma_f32_16x16x32_bf16 v[28:31], v[156:159], v[180:183], v[28:31]
	v_mfma_f32_16x16x32_bf16 v[24:27], v[164:167], v[180:183], v[24:27]
	v_mfma_f32_16x16x32_bf16 v[12:15], v[156:159], v[188:191], v[12:15]
	v_mfma_f32_16x16x32_bf16 v[8:11], v[164:167], v[188:191], v[8:11]
	v_mfma_f32_16x16x32_bf16 v[4:7], v[156:159], v[200:203], v[4:7]
	v_mfma_f32_16x16x32_bf16 v[0:3], v[164:167], v[200:203], v[0:3]
	v_mfma_f32_16x16x32_bf16 v[44:47], v[160:163], v[176:179], v[44:47]
	v_mfma_f32_16x16x32_bf16 v[40:43], v[168:171], v[176:179], v[40:43]
	v_mfma_f32_16x16x32_bf16 v[28:31], v[160:163], v[184:187], v[28:31]
	v_mfma_f32_16x16x32_bf16 v[24:27], v[168:171], v[184:187], v[24:27]
	v_mfma_f32_16x16x32_bf16 v[12:15], v[160:163], v[192:195], v[12:15]
	v_mfma_f32_16x16x32_bf16 v[8:11], v[168:171], v[192:195], v[8:11]
	v_mfma_f32_16x16x32_bf16 v[4:7], v[160:163], v[204:207], v[4:7]
	v_mfma_f32_16x16x32_bf16 v[0:3], v[168:171], v[204:207], v[0:3]
	s_setprio 0
	s_barrier
	s_add_i32 s37, s37, 2
	s_add_u32 s14, s14, 0x100
	s_addc_u32 s15, s15, 0
	s_add_u32 s35, s35, 0x100
	s_addc_u32 s36, s36, 0
	s_cmp_gt_u32 s37, 13
	s_cbranch_scc0 .LBB0_349
	s_and_b64 vcc, exec, s[2:3]
	s_cbranch_vccz .LBB0_352
	s_barrier

; #define PG8_STAGE(bufoff, gbase, voff) do { _Pragma("unroll") for (int _i = 0; _i < 2; ++_i) \
;         __builtin_amdgcn_global_load_lds((const unsigned*)((const char*)(gbase) + (voff)[_i]), (LAS unsigned*)(lds + (bufoff) + ldsw + _i * 8192), 16, 0, 0); } while (0)
; #define PG8_LDA(dst, b, h) do { _Pragma("unroll") for (int m = 0; m < 4; ++m) _Pragma("unroll") for (int k = 0; k < 2; ++k) dst[m][k] = *(const LAS bf16x8*)(lds + PG8_SA(b, h) + aoff + m * 2048 + k * 1024); } while (0)
; #define PG8_LDB(dst, b, h) do { _Pragma("unroll") for (int n = 0; n < 2; ++n) _Pragma("unroll") for (int k = 0; k < 2; ++k) dst[n][k] = *(const LAS bf16x8*)(lds + PG8_SB(b, h) + boff + n * 2048 + k * 1024); } while (0)
; #define PG8_MMA(ai, bj, At, Bt) do { __builtin_amdgcn_s_setprio(1); _Pragma("unroll") for (int m = 0; m < 4; ++m) _Pragma("unroll") for (int n = 0; n < 2; ++n) _Pragma("unroll") for (int k = 0; k < 2; ++k) \
;         acc[ai][bj][m][n] = __builtin_amdgcn_mfma_f32_16x16x32_bf16(Bt[n][k], At[m][k], acc[ai][bj][m][n], 0, 0, 0); __builtin_amdgcn_s_setprio(0); } while (0)
; #define PG8_WAIT_V(n) asm volatile("s_waitcnt vmcnt(" #n ")" ::: "memory")
; #define PG8_WAIT_L(n) asm volatile("s_waitcnt lgkmcnt(" #n ")" ::: "memory")
; #define PG8_BAR __builtin_amdgcn_s_barrier()
; #define PG8_SCHED __builtin_amdgcn_sched_barrier(0)
; template <class Epi, int N_, int K_, int LDA_>
; __device__ __forceinline__ void gemm_phase(LAS unsigned char* lds, const Gemm g, const Epi& E) {
;     ...
;         for (int t = 0; t < nt; t += 2) {
;             const bool last = (t == nt - 2);
;             const char* a1 = cA + (size_t)(t + 1) * kstep;
;             const char* a2 = last ? nA : cA + (size_t)(t + 2) * kstep; const char* b2 = last ? nB : cB + (size_t)(t + 2) * kstep;
;             const char* a3 = a2 + kstep; const char* b3 = b2 + kstep;
;             PG8_LDB(B0, 0, 0); PG8_LDB(B1, 0, 1); PG8_SCHED; PG8_LDA(At, 0, 0); PG8_STAGE(PG8_SA(1, 1), a1 + hstepA, voffA);
;             PG8_WAIT_V(8); PG8_WAIT_L(0); PG8_BAR; PG8_MMA(0, 0, At, B0); PG8_MMA(0, 1, At, B1); PG8_BAR; PG8_SCHED;
;             PG8_LDA(At, 0, 1); PG8_STAGE(PG8_SB(0, 0), b2, voffB); PG8_STAGE(PG8_SB(0, 1), b2 + hstepB, voffB); PG8_STAGE(PG8_SA(0, 0), a2, voffA);
.LBB0_1021:
	s_add_u32 s8, s0, 0x100
	s_addc_u32 s9, s1, 0
	s_add_i32 s45, 0, 0x10000
	s_cmp_eq_u32 s27, 28
	s_cselect_b32 s25, s15, s9
	s_cselect_b32 s24, s14, s8
	s_cselect_b32 s23, s13, s26
	s_cselect_b32 s22, s19, s21
	s_add_i32 s48, 0, 0x14000
	v_add_u32_e32 v140, s45, v212
	v_add_u32_e32 v156, s48, v212
	ds_read_b128 v[128:131], v140
	ds_read_b128 v[132:135], v140 offset:1024
	ds_read_b128 v[136:139], v140 offset:2048
	ds_read_b128 v[140:143], v140 offset:3072
	ds_read_b128 v[144:147], v156
	ds_read_b128 v[148:151], v156 offset:1024
	ds_read_b128 v[152:155], v156 offset:2048
	ds_read_b128 v[156:159], v156 offset:3072
	v_lshl_add_u64 v[194:195], s[0:1], 0, v[182:183]
	s_add_i32 m0, s29, 0xc000
	ds_read_b128 v[160:163], v213
	ds_read_b128 v[164:167], v213 offset:1024
	ds_read_b128 v[168:171], v213 offset:2048
	ds_read_b128 v[172:175], v213 offset:3072
	ds_read_b128 v[186:189], v213 offset:4096
	ds_read_b128 v[190:193], v213 offset:5120
	ds_read_b128 v[200:203], v213 offset:6144
	ds_read_b128 v[204:207], v213 offset:7168
	global_load_lds_dwordx4 v[194:195], off
	v_lshl_add_u64 v[194:195], s[0:1], 0, v[184:185]
	s_add_i32 m0, s29, 0xe000
	s_nop 0
	global_load_lds_dwordx4 v[194:195], off
	s_waitcnt vmcnt(8)
	s_waitcnt lgkmcnt(0)
	s_barrier
	s_setprio 1
	v_mfma_f32_16x16x32_bf16 v[52:55], v[128:131], v[160:163], v[52:55]
	v_mfma_f32_16x16x32_bf16 v[56:59], v[136:139], v[160:163], v[56:59]
	v_mfma_f32_16x16x32_bf16 v[84:87], v[128:131], v[168:171], v[84:87]
	v_mfma_f32_16x16x32_bf16 v[92:95], v[136:139], v[168:171], v[92:95]
	v_mfma_f32_16x16x32_bf16 v[100:103], v[128:131], v[186:189], v[100:103]
	v_mfma_f32_16x16x32_bf16 v[104:107], v[136:139], v[186:189], v[104:107]
	v_mfma_f32_16x16x32_bf16 v[124:127], v[128:131], v[200:203], v[124:127]
	v_mfma_f32_16x16x32_bf16 v[120:123], v[136:139], v[200:203], v[120:123]
	v_mfma_f32_16x16x32_bf16 v[52:55], v[132:135], v[164:167], v[52:55]
	v_mfma_f32_16x16x32_bf16 v[56:59], v[140:143], v[164:167], v[56:59]
	v_mfma_f32_16x16x32_bf16 v[84:87], v[132:135], v[172:175], v[84:87]
	v_mfma_f32_16x16x32_bf16 v[92:95], v[140:143], v[172:175], v[92:95]
	v_mfma_f32_16x16x32_bf16 v[100:103], v[132:135], v[190:193], v[100:103]
	v_mfma_f32_16x16x32_bf16 v[104:107], v[140:143], v[190:193], v[104:107]
	v_mfma_f32_16x16x32_bf16 v[124:127], v[132:135], v[204:207], v[124:127]
	v_mfma_f32_16x16x32_bf16 v[120:123], v[140:143], v[204:207], v[120:123]
	s_setprio 0
	s_setprio 1
	v_mfma_f32_16x16x32_bf16 v[64:67], v[144:147], v[160:163], v[64:67]
	v_mfma_f32_16x16x32_bf16 v[72:75], v[152:155], v[160:163], v[72:75]
	v_mfma_f32_16x16x32_bf16 v[80:83], v[144:147], v[168:171], v[80:83]
	v_mfma_f32_16x16x32_bf16 v[96:99], v[152:155], v[168:171], v[96:99]
	v_mfma_f32_16x16x32_bf16 v[108:111], v[144:147], v[186:189], v[108:111]
	v_mfma_f32_16x16x32_bf16 v[116:119], v[152:155], v[186:189], v[116:119]
	v_mfma_f32_16x16x32_bf16 v[112:115], v[144:147], v[200:203], v[112:115]
	v_mfma_f32_16x16x32_bf16 v[88:91], v[152:155], v[200:203], v[88:91]
	v_mfma_f32_16x16x32_bf16 v[64:67], v[148:151], v[164:167], v[64:67]
	v_mfma_f32_16x16x32_bf16 v[72:75], v[156:159], v[164:167], v[72:75]
	v_mfma_f32_16x16x32_bf16 v[80:83], v[148:151], v[172:175], v[80:83]
	v_mfma_f32_16x16x32_bf16 v[96:99], v[156:159], v[172:175], v[96:99]
	v_mfma_f32_16x16x32_bf16 v[108:111], v[148:151], v[190:193], v[108:111]
	v_mfma_f32_16x16x32_bf16 v[116:119], v[156:159], v[190:193], v[116:119]
	v_mfma_f32_16x16x32_bf16 v[112:115], v[148:151], v[204:207], v[112:115]
	v_mfma_f32_16x16x32_bf16 v[88:91], v[156:159], v[204:207], v[88:91]
	s_setprio 0
	s_barrier
	s_add_i32 s0, s45, s28
	v_lshl_add_u64 v[194:195], s[22:23], 0, v[196:197]
	s_mov_b32 m0, s0
	ds_read_b128 v[160:163], v213 offset:16384
	ds_read_b128 v[164:167], v213 offset:17408
	ds_read_b128 v[168:171], v213 offset:18432
	ds_read_b128 v[172:175], v213 offset:19456
	ds_read_b128 v[186:189], v213 offset:20480
	ds_read_b128 v[190:193], v213 offset:21504
	ds_read_b128 v[200:203], v213 offset:22528
	ds_read_b128 v[204:207], v213 offset:23552
	global_load_lds_dwordx4 v[194:195], off
	s_add_i32 m0, s0, 0x2000
	s_add_u32 s0, s22, 0x80000
	v_lshl_add_u64 v[208:209], s[22:23], 0, v[176:177]
	s_addc_u32 s1, s23, 0
	s_add_i32 s45, s48, s28
	global_load_lds_dwordx4 v[208:209], off
	v_lshl_add_u64 v[210:211], s[0:1], 0, v[196:197]
	s_mov_b32 m0, s45
	v_lshl_add_u64 v[214:215], s[24:25], 0, v[178:179]
	global_load_lds_dwordx4 v[210:211], off
	v_lshl_add_u64 v[210:211], s[0:1], 0, v[176:177]
	s_add_i32 m0, s45, 0x2000
	s_nop 0
	global_load_lds_dwordx4 v[210:211], off
	v_lshl_add_u64 v[210:211], s[24:25], 0, v[180:181]
	s_mov_b32 m0, s29
	s_nop 0
	global_load_lds_dwordx4 v[210:211], off
	s_mov_b32 m0, s30
	s_nop 0
	global_load_lds_dwordx4 v[214:215], off
	s_waitcnt vmcnt(8)
	s_waitcnt lgkmcnt(0)
	s_barrier
; #define PG8_STAGE(bufoff, gbase, voff) do { _Pragma("unroll") for (int _i = 0; _i < 2; ++_i) \
;         __builtin_amdgcn_global_load_lds((const unsigned*)((const char*)(gbase) + (voff)[_i]), (LAS unsigned*)(lds + (bufoff) + ldsw + _i * 8192), 16, 0, 0); } while (0)
; #define PG8_LDA(dst, b, h) do { _Pragma("unroll") for (int m = 0; m < 4; ++m) _Pragma("unroll") for (int k = 0; k < 2; ++k) dst[m][k] = *(const LAS bf16x8*)(lds + PG8_SA(b, h) + aoff + m * 2048 + k * 1024); } while (0)
; #define PG8_LDB(dst, b, h) do { _Pragma("unroll") for (int n = 0; n < 2; ++n) _Pragma("unroll") for (int k = 0; k < 2; ++k) dst[n][k] = *(const LAS bf16x8*)(lds + PG8_SB(b, h) + boff + n * 2048 + k * 1024); } while (0)
; #define PG8_MMA(ai, bj, At, Bt) do { __builtin_amdgcn_s_setprio(1); _Pragma("unroll") for (int m = 0; m < 4; ++m) _Pragma("unroll") for (int n = 0; n < 2; ++n) _Pragma("unroll") for (int k = 0; k < 2; ++k) \
;         acc[ai][bj][m][n] = __builtin_amdgcn_mfma_f32_16x16x32_bf16(Bt[n][k], At[m][k], acc[ai][bj][m][n], 0, 0, 0); __builtin_amdgcn_s_setprio(0); } while (0)
; #define PG8_WAIT_V(n) asm volatile("s_waitcnt vmcnt(" #n ")" ::: "memory")
; #define PG8_WAIT_L(n) asm volatile("s_waitcnt lgkmcnt(" #n ")" ::: "memory")
; #define PG8_BAR __builtin_amdgcn_s_barrier()
; #define PG8_SCHED __builtin_amdgcn_sched_barrier(0)
; template <class Epi, int N_, int K_, int LDA_>
; __device__ __forceinline__ void gemm_phase(LAS unsigned char* lds, const Gemm g, const Epi& E) {
;     ...
;             PG8_WAIT_V(8); PG8_WAIT_L(0); PG8_BAR; PG8_MMA(1, 0, At, B0); PG8_MMA(1, 1, At, B1); PG8_BAR; PG8_SCHED;
;             PG8_LDB(B0, 1, 0); PG8_LDB(B1, 1, 1); PG8_SCHED; PG8_LDA(At, 1, 0); PG8_STAGE(PG8_SA(0, 1), a2 + hstepA, voffA);
;             PG8_WAIT_V(8); PG8_WAIT_L(0); PG8_BAR; PG8_MMA(0, 0, At, B0); PG8_MMA(0, 1, At, B1); PG8_BAR; PG8_SCHED;
	s_setprio 1
	v_mfma_f32_16x16x32_bf16 v[76:79], v[128:131], v[160:163], v[76:79]
	v_mfma_f32_16x16x32_bf16 v[68:71], v[136:139], v[160:163], v[68:71]
	v_mfma_f32_16x16x32_bf16 v[44:47], v[128:131], v[168:171], v[44:47]
	v_mfma_f32_16x16x32_bf16 v[40:43], v[136:139], v[168:171], v[40:43]
	v_mfma_f32_16x16x32_bf16 v[28:31], v[128:131], v[186:189], v[28:31]
	v_mfma_f32_16x16x32_bf16 v[24:27], v[136:139], v[186:189], v[24:27]
	v_mfma_f32_16x16x32_bf16 v[12:15], v[128:131], v[200:203], v[12:15]
	v_mfma_f32_16x16x32_bf16 v[8:11], v[136:139], v[200:203], v[8:11]
	v_mfma_f32_16x16x32_bf16 v[76:79], v[132:135], v[164:167], v[76:79]
	v_mfma_f32_16x16x32_bf16 v[68:71], v[140:143], v[164:167], v[68:71]
	v_mfma_f32_16x16x32_bf16 v[44:47], v[132:135], v[172:175], v[44:47]
	v_mfma_f32_16x16x32_bf16 v[40:43], v[140:143], v[172:175], v[40:43]
	v_mfma_f32_16x16x32_bf16 v[28:31], v[132:135], v[190:193], v[28:31]
	v_mfma_f32_16x16x32_bf16 v[24:27], v[140:143], v[190:193], v[24:27]
	v_mfma_f32_16x16x32_bf16 v[12:15], v[132:135], v[204:207], v[12:15]
	v_mfma_f32_16x16x32_bf16 v[8:11], v[140:143], v[204:207], v[8:11]
	s_setprio 0
	s_setprio 1
	v_mfma_f32_16x16x32_bf16 v[60:63], v[144:147], v[160:163], v[60:63]
	v_mfma_f32_16x16x32_bf16 v[48:51], v[152:155], v[160:163], v[48:51]
	v_mfma_f32_16x16x32_bf16 v[36:39], v[144:147], v[168:171], v[36:39]
	v_mfma_f32_16x16x32_bf16 v[32:35], v[152:155], v[168:171], v[32:35]
	v_mfma_f32_16x16x32_bf16 v[20:23], v[144:147], v[186:189], v[20:23]
	v_mfma_f32_16x16x32_bf16 v[16:19], v[152:155], v[186:189], v[16:19]
	v_mfma_f32_16x16x32_bf16 v[4:7], v[144:147], v[200:203], v[4:7]
	v_mfma_f32_16x16x32_bf16 v[0:3], v[152:155], v[200:203], v[0:3]
	v_mfma_f32_16x16x32_bf16 v[60:63], v[148:151], v[164:167], v[60:63]
	v_mfma_f32_16x16x32_bf16 v[48:51], v[156:159], v[164:167], v[48:51]
	v_mfma_f32_16x16x32_bf16 v[36:39], v[148:151], v[172:175], v[36:39]
	v_mfma_f32_16x16x32_bf16 v[32:35], v[156:159], v[172:175], v[32:35]
	v_mfma_f32_16x16x32_bf16 v[20:23], v[148:151], v[190:193], v[20:23]
	v_mfma_f32_16x16x32_bf16 v[16:19], v[156:159], v[190:193], v[16:19]
	v_mfma_f32_16x16x32_bf16 v[4:7], v[148:151], v[204:207], v[4:7]
	v_mfma_f32_16x16x32_bf16 v[0:3], v[156:159], v[204:207], v[0:3]
	s_setprio 0
	s_barrier
	s_add_i32 s45, 0, 0x18000
	s_add_i32 s48, 0, 0x1c000
	v_add_u32_e32 v140, s45, v212
	v_add_u32_e32 v156, s48, v212
	ds_read_b128 v[128:131], v140
	ds_read_b128 v[132:135], v140 offset:1024
	ds_read_b128 v[136:139], v140 offset:2048
	ds_read_b128 v[140:143], v140 offset:3072
	ds_read_b128 v[144:147], v156
	ds_read_b128 v[148:151], v156 offset:1024
	ds_read_b128 v[152:155], v156 offset:2048
	ds_read_b128 v[156:159], v156 offset:3072
	s_add_u32 s0, s24, 0x184000
	s_addc_u32 s1, s25, 0
	s_mov_b32 m0, s31
	v_lshl_add_u64 v[216:217], s[0:1], 0, v[180:181]
	ds_read_b128 v[160:163], v213 offset:32768
	ds_read_b128 v[164:167], v213 offset:33792
	ds_read_b128 v[168:171], v213 offset:34816
	ds_read_b128 v[172:175], v213 offset:35840
	ds_read_b128 v[186:189], v213 offset:36864
	ds_read_b128 v[190:193], v213 offset:37888
	ds_read_b128 v[200:203], v213 offset:38912
	ds_read_b128 v[204:207], v213 offset:39936
	global_load_lds_dwordx4 v[216:217], off
	v_lshl_add_u64 v[216:217], s[0:1], 0, v[178:179]
	s_mov_b32 m0, s33
	s_nop 0
	global_load_lds_dwordx4 v[216:217], off
	s_waitcnt vmcnt(8)
	s_waitcnt lgkmcnt(0)
	s_barrier
	s_setprio 1
	v_mfma_f32_16x16x32_bf16 v[52:55], v[128:131], v[160:163], v[52:55]
	v_mfma_f32_16x16x32_bf16 v[56:59], v[136:139], v[160:163], v[56:59]
	v_mfma_f32_16x16x32_bf16 v[84:87], v[128:131], v[168:171], v[84:87]
	v_mfma_f32_16x16x32_bf16 v[92:95], v[136:139], v[168:171], v[92:95]
	v_mfma_f32_16x16x32_bf16 v[100:103], v[128:131], v[186:189], v[100:103]
	v_mfma_f32_16x16x32_bf16 v[104:107], v[136:139], v[186:189], v[104:107]
	v_mfma_f32_16x16x32_bf16 v[124:127], v[128:131], v[200:203], v[124:127]
	v_mfma_f32_16x16x32_bf16 v[120:123], v[136:139], v[200:203], v[120:123]
	v_mfma_f32_16x16x32_bf16 v[52:55], v[132:135], v[164:167], v[52:55]
	v_mfma_f32_16x16x32_bf16 v[56:59], v[140:143], v[164:167], v[56:59]
	v_mfma_f32_16x16x32_bf16 v[84:87], v[132:135], v[172:175], v[84:87]
	v_mfma_f32_16x16x32_bf16 v[92:95], v[140:143], v[172:175], v[92:95]
	v_mfma_f32_16x16x32_bf16 v[100:103], v[132:135], v[190:193], v[100:103]
	v_mfma_f32_16x16x32_bf16 v[104:107], v[140:143], v[190:193], v[104:107]
	v_mfma_f32_16x16x32_bf16 v[124:127], v[132:135], v[204:207], v[124:127]
	v_mfma_f32_16x16x32_bf16 v[120:123], v[140:143], v[204:207], v[120:123]
	s_setprio 0
	s_setprio 1
	v_mfma_f32_16x16x32_bf16 v[64:67], v[144:147], v[160:163], v[64:67]
	v_mfma_f32_16x16x32_bf16 v[72:75], v[152:155], v[160:163], v[72:75]
	v_mfma_f32_16x16x32_bf16 v[80:83], v[144:147], v[168:171], v[80:83]
	v_mfma_f32_16x16x32_bf16 v[96:99], v[152:155], v[168:171], v[96:99]
	v_mfma_f32_16x16x32_bf16 v[108:111], v[144:147], v[186:189], v[108:111]
	v_mfma_f32_16x16x32_bf16 v[116:119], v[152:155], v[186:189], v[116:119]
	v_mfma_f32_16x16x32_bf16 v[112:115], v[144:147], v[200:203], v[112:115]
	v_mfma_f32_16x16x32_bf16 v[88:91], v[152:155], v[200:203], v[88:91]
	v_mfma_f32_16x16x32_bf16 v[64:67], v[148:151], v[164:167], v[64:67]
	v_mfma_f32_16x16x32_bf16 v[72:75], v[156:159], v[164:167], v[72:75]
	v_mfma_f32_16x16x32_bf16 v[80:83], v[148:151], v[172:175], v[80:83]
	v_mfma_f32_16x16x32_bf16 v[96:99], v[156:159], v[172:175], v[96:99]
	v_mfma_f32_16x16x32_bf16 v[108:111], v[148:151], v[190:193], v[108:111]
	v_mfma_f32_16x16x32_bf16 v[116:119], v[156:159], v[190:193], v[116:119]
	v_mfma_f32_16x16x32_bf16 v[112:115], v[148:151], v[204:207], v[112:115]
	v_mfma_f32_16x16x32_bf16 v[88:91], v[156:159], v[204:207], v[88:91]
	s_setprio 0
	s_barrier
; #define PG8_STAGE(bufoff, gbase, voff) do { _Pragma("unroll") for (int _i = 0; _i < 2; ++_i) \
;         __builtin_amdgcn_global_load_lds((const unsigned*)((const char*)(gbase) + (voff)[_i]), (LAS unsigned*)(lds + (bufoff) + ldsw + _i * 8192), 16, 0, 0); } while (0)
; #define PG8_LDA(dst, b, h) do { _Pragma("unroll") for (int m = 0; m < 4; ++m) _Pragma("unroll") for (int k = 0; k < 2; ++k) dst[m][k] = *(const LAS bf16x8*)(lds + PG8_SA(b, h) + aoff + m * 2048 + k * 1024); } while (0)
; #define PG8_MMA(ai, bj, At, Bt) do { __builtin_amdgcn_s_setprio(1); _Pragma("unroll") for (int m = 0; m < 4; ++m) _Pragma("unroll") for (int n = 0; n < 2; ++n) _Pragma("unroll") for (int k = 0; k < 2; ++k) \
;         acc[ai][bj][m][n] = __builtin_amdgcn_mfma_f32_16x16x32_bf16(Bt[n][k], At[m][k], acc[ai][bj][m][n], 0, 0, 0); __builtin_amdgcn_s_setprio(0); } while (0)
; #define PG8_WAIT_V(n) asm volatile("s_waitcnt vmcnt(" #n ")" ::: "memory")
; #define PG8_WAIT_L(n) asm volatile("s_waitcnt lgkmcnt(" #n ")" ::: "memory")
; #define PG8_BAR __builtin_amdgcn_s_barrier()
; #define PG8_SCHED __builtin_amdgcn_sched_barrier(0)
; template <class Epi, int N_, int K_, int LDA_>
; __device__ __forceinline__ void gemm_phase(LAS unsigned char* lds, const Gemm g, const Epi& E) {
;     ...
;             PG8_LDA(At, 1, 1); PG8_STAGE(PG8_SB(1, 0), b3, voffB); PG8_STAGE(PG8_SB(1, 1), b3 + hstepB, voffB); PG8_STAGE(PG8_SA(1, 0), a3, voffA);
;             PG8_WAIT_V(8); PG8_WAIT_L(0); PG8_BAR; PG8_MMA(1, 0, At, B0); PG8_MMA(1, 1, At, B1); PG8_BAR; PG8_SCHED;
;         }
;         if (wr == 0) PG8_BAR;
	s_add_i32 s0, s45, s28
	v_lshl_add_u64 v[194:195], v[194:195], 0, s[56:57]
	s_mov_b32 m0, s0
	ds_read_b128 v[160:163], v213 offset:49152
	ds_read_b128 v[164:167], v213 offset:50176
	ds_read_b128 v[168:171], v213 offset:51200
	ds_read_b128 v[172:175], v213 offset:52224
	ds_read_b128 v[186:189], v213 offset:53248
	ds_read_b128 v[190:193], v213 offset:54272
	ds_read_b128 v[200:203], v213 offset:55296
	ds_read_b128 v[204:207], v213 offset:56320
	global_load_lds_dwordx4 v[194:195], off
	s_add_i32 m0, s0, 0x2000
	s_add_u32 s0, s22, 0x80080
	v_lshl_add_u64 v[194:195], v[208:209], 0, s[56:57]
	s_addc_u32 s1, s23, 0
	s_add_i32 s22, s48, s28
	global_load_lds_dwordx4 v[194:195], off
	v_lshl_add_u64 v[194:195], s[0:1], 0, v[196:197]
	s_mov_b32 m0, s22
	s_nop 0
	global_load_lds_dwordx4 v[194:195], off
	v_lshl_add_u64 v[194:195], s[0:1], 0, v[176:177]
	s_add_i32 m0, s22, 0x2000
	s_nop 0
	global_load_lds_dwordx4 v[194:195], off
	v_lshl_add_u64 v[194:195], v[210:211], 0, s[56:57]
	s_mov_b32 m0, s36
	s_nop 0
	global_load_lds_dwordx4 v[194:195], off
	v_lshl_add_u64 v[194:195], v[214:215], 0, s[56:57]
	s_mov_b32 m0, s37
	s_nop 0
	global_load_lds_dwordx4 v[194:195], off
	s_waitcnt vmcnt(8)
	s_waitcnt lgkmcnt(0)
	s_barrier
	s_setprio 1
	v_mfma_f32_16x16x32_bf16 v[76:79], v[128:131], v[160:163], v[76:79]
	v_mfma_f32_16x16x32_bf16 v[68:71], v[136:139], v[160:163], v[68:71]
	v_mfma_f32_16x16x32_bf16 v[44:47], v[128:131], v[168:171], v[44:47]
	v_mfma_f32_16x16x32_bf16 v[40:43], v[136:139], v[168:171], v[40:43]
	v_mfma_f32_16x16x32_bf16 v[28:31], v[128:131], v[186:189], v[28:31]
	v_mfma_f32_16x16x32_bf16 v[24:27], v[136:139], v[186:189], v[24:27]
	v_mfma_f32_16x16x32_bf16 v[12:15], v[128:131], v[200:203], v[12:15]
	v_mfma_f32_16x16x32_bf16 v[8:11], v[136:139], v[200:203], v[8:11]
	v_mfma_f32_16x16x32_bf16 v[76:79], v[132:135], v[164:167], v[76:79]
	v_mfma_f32_16x16x32_bf16 v[68:71], v[140:143], v[164:167], v[68:71]
	v_mfma_f32_16x16x32_bf16 v[44:47], v[132:135], v[172:175], v[44:47]
	v_mfma_f32_16x16x32_bf16 v[40:43], v[140:143], v[172:175], v[40:43]
	v_mfma_f32_16x16x32_bf16 v[28:31], v[132:135], v[190:193], v[28:31]
	v_mfma_f32_16x16x32_bf16 v[24:27], v[140:143], v[190:193], v[24:27]
	v_mfma_f32_16x16x32_bf16 v[12:15], v[132:135], v[204:207], v[12:15]
	v_mfma_f32_16x16x32_bf16 v[8:11], v[140:143], v[204:207], v[8:11]
	s_setprio 0
	s_setprio 1
	v_mfma_f32_16x16x32_bf16 v[60:63], v[144:147], v[160:163], v[60:63]
	v_mfma_f32_16x16x32_bf16 v[48:51], v[152:155], v[160:163], v[48:51]
	v_mfma_f32_16x16x32_bf16 v[36:39], v[144:147], v[168:171], v[36:39]
	v_mfma_f32_16x16x32_bf16 v[32:35], v[152:155], v[168:171], v[32:35]
	v_mfma_f32_16x16x32_bf16 v[20:23], v[144:147], v[186:189], v[20:23]
	v_mfma_f32_16x16x32_bf16 v[16:19], v[152:155], v[186:189], v[16:19]
	v_mfma_f32_16x16x32_bf16 v[4:7], v[144:147], v[200:203], v[4:7]
	v_mfma_f32_16x16x32_bf16 v[0:3], v[152:155], v[200:203], v[0:3]
	v_mfma_f32_16x16x32_bf16 v[60:63], v[148:151], v[164:167], v[60:63]
	v_mfma_f32_16x16x32_bf16 v[48:51], v[156:159], v[164:167], v[48:51]
	v_mfma_f32_16x16x32_bf16 v[36:39], v[148:151], v[172:175], v[36:39]
	v_mfma_f32_16x16x32_bf16 v[32:35], v[156:159], v[172:175], v[32:35]
	v_mfma_f32_16x16x32_bf16 v[20:23], v[148:151], v[190:193], v[20:23]
	v_mfma_f32_16x16x32_bf16 v[16:19], v[156:159], v[190:193], v[16:19]
	v_mfma_f32_16x16x32_bf16 v[4:7], v[148:151], v[204:207], v[4:7]
	v_mfma_f32_16x16x32_bf16 v[0:3], v[156:159], v[204:207], v[0:3]
	s_setprio 0
	s_barrier
	s_add_i32 s27, s27, 2
	s_add_u32 s21, s21, 0x100
	s_addc_u32 s26, s26, 0
	s_cmp_gt_u32 s27, 29
	s_mov_b64 s[0:1], s[8:9]
	s_cbranch_scc0 .LBB0_1021
	s_and_b64 vcc, exec, s[10:11]
	s_cbranch_vccz .LBB0_1024
	s_barrier

; #define PG8_STAGE(bufoff, gbase, voff) do { _Pragma("unroll") for (int _i = 0; _i < 2; ++_i) \
;         __builtin_amdgcn_global_load_lds((const unsigned*)((const char*)(gbase) + (voff)[_i]), (LAS unsigned*)(lds + (bufoff) + ldsw + _i * 8192), 16, 0, 0); } while (0)
; #define PG8_LDA(dst, b, h) do { _Pragma("unroll") for (int m = 0; m < 4; ++m) _Pragma("unroll") for (int k = 0; k < 2; ++k) dst[m][k] = *(const LAS bf16x8*)(lds + PG8_SA(b, h) + aoff + m * 2048 + k * 1024); } while (0)
; #define PG8_LDB(dst, b, h) do { _Pragma("unroll") for (int n = 0; n < 2; ++n) _Pragma("unroll") for (int k = 0; k < 2; ++k) dst[n][k] = *(const LAS bf16x8*)(lds + PG8_SB(b, h) + boff + n * 2048 + k * 1024); } while (0)
; #define PG8_MMA(ai, bj, At, Bt) do { __builtin_amdgcn_s_setprio(1); _Pragma("unroll") for (int m = 0; m < 4; ++m) _Pragma("unroll") for (int n = 0; n < 2; ++n) _Pragma("unroll") for (int k = 0; k < 2; ++k) \
;         acc[ai][bj][m][n] = __builtin_amdgcn_mfma_f32_16x16x32_bf16(Bt[n][k], At[m][k], acc[ai][bj][m][n], 0, 0, 0); __builtin_amdgcn_s_setprio(0); } while (0)
; #define PG8_WAIT_V(n) asm volatile("s_waitcnt vmcnt(" #n ")" ::: "memory")
; #define PG8_WAIT_L(n) asm volatile("s_waitcnt lgkmcnt(" #n ")" ::: "memory")
; #define PG8_BAR __builtin_amdgcn_s_barrier()
; #define PG8_SCHED __builtin_amdgcn_sched_barrier(0)
; template <class Epi, int N_, int K_, int LDA_>
; __device__ __forceinline__ void gemm_phase(LAS unsigned char* lds, const Gemm g, const Epi& E) {
;     ...
;         for (int t = 0; t < nt; t += 2) {
;             const bool last = (t == nt - 2);
;             const char* a1 = cA + (size_t)(t + 1) * kstep;
;             const char* a2 = last ? nA : cA + (size_t)(t + 2) * kstep; const char* b2 = last ? nB : cB + (size_t)(t + 2) * kstep;
;             const char* a3 = a2 + kstep; const char* b3 = b2 + kstep;
;             PG8_LDB(B0, 0, 0); PG8_LDB(B1, 0, 1); PG8_SCHED; PG8_LDA(At, 0, 0); PG8_STAGE(PG8_SA(1, 1), a1 + hstepA, voffA);
;             PG8_WAIT_V(8); PG8_WAIT_L(0); PG8_BAR; PG8_MMA(0, 0, At, B0); PG8_MMA(0, 1, At, B1); PG8_BAR; PG8_SCHED;
;             PG8_LDA(At, 0, 1); PG8_STAGE(PG8_SB(0, 0), b2, voffB); PG8_STAGE(PG8_SB(0, 1), b2 + hstepB, voffB); PG8_STAGE(PG8_SA(0, 0), a2, voffA);
.LBB0_1069:
	s_add_u32 s20, s0, 0xfffc0080
	s_addc_u32 s21, s1, -1
	s_add_i32 s27, 0, 0x10000
	s_cmp_eq_u32 s26, 12
	s_cselect_b32 s23, s11, s21
	s_cselect_b32 s22, s17, s20
	s_cselect_b32 s21, s9, s25
	s_cselect_b32 s20, s19, s24
	s_add_i32 s48, 0, 0x14000
	v_add_u32_e32 v140, s27, v212
	v_add_u32_e32 v156, s48, v212
	ds_read_b128 v[128:131], v140
	ds_read_b128 v[132:135], v140 offset:1024
	ds_read_b128 v[136:139], v140 offset:2048
	ds_read_b128 v[140:143], v140 offset:3072
	ds_read_b128 v[144:147], v156
	ds_read_b128 v[148:151], v156 offset:1024
	ds_read_b128 v[152:155], v156 offset:2048
	ds_read_b128 v[156:159], v156 offset:3072
	v_lshl_add_u64 v[194:195], s[0:1], 0, v[182:183]
	s_add_i32 m0, s29, 0xc000
	ds_read_b128 v[160:163], v213
	ds_read_b128 v[164:167], v213 offset:1024
	ds_read_b128 v[168:171], v213 offset:2048
	ds_read_b128 v[172:175], v213 offset:3072
	ds_read_b128 v[186:189], v213 offset:4096
	ds_read_b128 v[190:193], v213 offset:5120
	ds_read_b128 v[200:203], v213 offset:6144
	ds_read_b128 v[204:207], v213 offset:7168
	global_load_lds_dwordx4 v[194:195], off
	v_lshl_add_u64 v[194:195], s[0:1], 0, v[184:185]
	s_add_i32 m0, s29, 0xe000
	s_nop 0
	global_load_lds_dwordx4 v[194:195], off
	s_waitcnt vmcnt(8)
	s_waitcnt lgkmcnt(0)
	s_barrier
	s_setprio 1
	v_mfma_f32_16x16x32_bf16 v[52:55], v[128:131], v[160:163], v[52:55]
	v_mfma_f32_16x16x32_bf16 v[56:59], v[136:139], v[160:163], v[56:59]
	v_mfma_f32_16x16x32_bf16 v[84:87], v[128:131], v[168:171], v[84:87]
	v_mfma_f32_16x16x32_bf16 v[92:95], v[136:139], v[168:171], v[92:95]
	v_mfma_f32_16x16x32_bf16 v[100:103], v[128:131], v[186:189], v[100:103]
	v_mfma_f32_16x16x32_bf16 v[104:107], v[136:139], v[186:189], v[104:107]
	v_mfma_f32_16x16x32_bf16 v[124:127], v[128:131], v[200:203], v[124:127]
	v_mfma_f32_16x16x32_bf16 v[120:123], v[136:139], v[200:203], v[120:123]
	v_mfma_f32_16x16x32_bf16 v[52:55], v[132:135], v[164:167], v[52:55]
	v_mfma_f32_16x16x32_bf16 v[56:59], v[140:143], v[164:167], v[56:59]
	v_mfma_f32_16x16x32_bf16 v[84:87], v[132:135], v[172:175], v[84:87]
	v_mfma_f32_16x16x32_bf16 v[92:95], v[140:143], v[172:175], v[92:95]
	v_mfma_f32_16x16x32_bf16 v[100:103], v[132:135], v[190:193], v[100:103]
	v_mfma_f32_16x16x32_bf16 v[104:107], v[140:143], v[190:193], v[104:107]
	v_mfma_f32_16x16x32_bf16 v[124:127], v[132:135], v[204:207], v[124:127]
	v_mfma_f32_16x16x32_bf16 v[120:123], v[140:143], v[204:207], v[120:123]
	s_setprio 0
	s_setprio 1
	v_mfma_f32_16x16x32_bf16 v[64:67], v[144:147], v[160:163], v[64:67]
	v_mfma_f32_16x16x32_bf16 v[72:75], v[152:155], v[160:163], v[72:75]
	v_mfma_f32_16x16x32_bf16 v[80:83], v[144:147], v[168:171], v[80:83]
	v_mfma_f32_16x16x32_bf16 v[96:99], v[152:155], v[168:171], v[96:99]
	v_mfma_f32_16x16x32_bf16 v[108:111], v[144:147], v[186:189], v[108:111]
	v_mfma_f32_16x16x32_bf16 v[116:119], v[152:155], v[186:189], v[116:119]
	v_mfma_f32_16x16x32_bf16 v[112:115], v[144:147], v[200:203], v[112:115]
	v_mfma_f32_16x16x32_bf16 v[88:91], v[152:155], v[200:203], v[88:91]
	v_mfma_f32_16x16x32_bf16 v[64:67], v[148:151], v[164:167], v[64:67]
	v_mfma_f32_16x16x32_bf16 v[72:75], v[156:159], v[164:167], v[72:75]
	v_mfma_f32_16x16x32_bf16 v[80:83], v[148:151], v[172:175], v[80:83]
	v_mfma_f32_16x16x32_bf16 v[96:99], v[156:159], v[172:175], v[96:99]
	v_mfma_f32_16x16x32_bf16 v[108:111], v[148:151], v[190:193], v[108:111]
	v_mfma_f32_16x16x32_bf16 v[116:119], v[156:159], v[190:193], v[116:119]
	v_mfma_f32_16x16x32_bf16 v[112:115], v[148:151], v[204:207], v[112:115]
	v_mfma_f32_16x16x32_bf16 v[88:91], v[156:159], v[204:207], v[88:91]
	s_setprio 0
	s_barrier
	s_add_i32 s27, s27, s28
	v_lshl_add_u64 v[194:195], s[20:21], 0, v[196:197]
	s_mov_b32 m0, s27
	ds_read_b128 v[160:163], v213 offset:16384
	ds_read_b128 v[164:167], v213 offset:17408
	ds_read_b128 v[168:171], v213 offset:18432
	ds_read_b128 v[172:175], v213 offset:19456
	ds_read_b128 v[186:189], v213 offset:20480
	ds_read_b128 v[190:193], v213 offset:21504
	ds_read_b128 v[200:203], v213 offset:22528
	ds_read_b128 v[204:207], v213 offset:23552
	global_load_lds_dwordx4 v[194:195], off
	s_add_i32 m0, s27, 0x2000
	s_add_u32 s44, s20, 0x40000
	v_lshl_add_u64 v[208:209], s[20:21], 0, v[176:177]
	s_addc_u32 s45, s21, 0
	s_add_i32 s27, s48, s28
	global_load_lds_dwordx4 v[208:209], off
	v_lshl_add_u64 v[210:211], s[44:45], 0, v[196:197]
	s_mov_b32 m0, s27
	v_lshl_add_u64 v[214:215], s[22:23], 0, v[178:179]
	global_load_lds_dwordx4 v[210:211], off
	v_lshl_add_u64 v[210:211], s[44:45], 0, v[176:177]
	s_add_i32 m0, s27, 0x2000
	s_nop 0
	global_load_lds_dwordx4 v[210:211], off
	v_lshl_add_u64 v[210:211], s[22:23], 0, v[180:181]
	s_mov_b32 m0, s29
	s_nop 0
	global_load_lds_dwordx4 v[210:211], off
	s_mov_b32 m0, s30
	s_nop 0
	global_load_lds_dwordx4 v[214:215], off
	s_waitcnt vmcnt(8)
	s_waitcnt lgkmcnt(0)
	s_barrier
; #define PG8_STAGE(bufoff, gbase, voff) do { _Pragma("unroll") for (int _i = 0; _i < 2; ++_i) \
;         __builtin_amdgcn_global_load_lds((const unsigned*)((const char*)(gbase) + (voff)[_i]), (LAS unsigned*)(lds + (bufoff) + ldsw + _i * 8192), 16, 0, 0); } while (0)
; #define PG8_LDA(dst, b, h) do { _Pragma("unroll") for (int m = 0; m < 4; ++m) _Pragma("unroll") for (int k = 0; k < 2; ++k) dst[m][k] = *(const LAS bf16x8*)(lds + PG8_SA(b, h) + aoff + m * 2048 + k * 1024); } while (0)
; #define PG8_LDB(dst, b, h) do { _Pragma("unroll") for (int n = 0; n < 2; ++n) _Pragma("unroll") for (int k = 0; k < 2; ++k) dst[n][k] = *(const LAS bf16x8*)(lds + PG8_SB(b, h) + boff + n * 2048 + k * 1024); } while (0)
; #define PG8_MMA(ai, bj, At, Bt) do { __builtin_amdgcn_s_setprio(1); _Pragma("unroll") for (int m = 0; m < 4; ++m) _Pragma("unroll") for (int n = 0; n < 2; ++n) _Pragma("unroll") for (int k = 0; k < 2; ++k) \
;         acc[ai][bj][m][n] = __builtin_amdgcn_mfma_f32_16x16x32_bf16(Bt[n][k], At[m][k], acc[ai][bj][m][n], 0, 0, 0); __builtin_amdgcn_s_setprio(0); } while (0)
; #define PG8_WAIT_V(n) asm volatile("s_waitcnt vmcnt(" #n ")" ::: "memory")
; #define PG8_WAIT_L(n) asm volatile("s_waitcnt lgkmcnt(" #n ")" ::: "memory")
; #define PG8_BAR __builtin_amdgcn_s_barrier()
; #define PG8_SCHED __builtin_amdgcn_sched_barrier(0)
; template <class Epi, int N_, int K_, int LDA_>
; __device__ __forceinline__ void gemm_phase(LAS unsigned char* lds, const Gemm g, const Epi& E) {
;     ...
;             PG8_WAIT_V(8); PG8_WAIT_L(0); PG8_BAR; PG8_MMA(1, 0, At, B0); PG8_MMA(1, 1, At, B1); PG8_BAR; PG8_SCHED;
;             PG8_LDB(B0, 1, 0); PG8_LDB(B1, 1, 1); PG8_SCHED; PG8_LDA(At, 1, 0); PG8_STAGE(PG8_SA(0, 1), a2 + hstepA, voffA);
;             PG8_WAIT_V(8); PG8_WAIT_L(0); PG8_BAR; PG8_MMA(0, 0, At, B0); PG8_MMA(0, 1, At, B1); PG8_BAR; PG8_SCHED;
	s_setprio 1
	v_mfma_f32_16x16x32_bf16 v[76:79], v[128:131], v[160:163], v[76:79]
	v_mfma_f32_16x16x32_bf16 v[68:71], v[136:139], v[160:163], v[68:71]
	v_mfma_f32_16x16x32_bf16 v[44:47], v[128:131], v[168:171], v[44:47]
	v_mfma_f32_16x16x32_bf16 v[40:43], v[136:139], v[168:171], v[40:43]
	v_mfma_f32_16x16x32_bf16 v[28:31], v[128:131], v[186:189], v[28:31]
	v_mfma_f32_16x16x32_bf16 v[24:27], v[136:139], v[186:189], v[24:27]
	v_mfma_f32_16x16x32_bf16 v[12:15], v[128:131], v[200:203], v[12:15]
	v_mfma_f32_16x16x32_bf16 v[8:11], v[136:139], v[200:203], v[8:11]
	v_mfma_f32_16x16x32_bf16 v[76:79], v[132:135], v[164:167], v[76:79]
	v_mfma_f32_16x16x32_bf16 v[68:71], v[140:143], v[164:167], v[68:71]
	v_mfma_f32_16x16x32_bf16 v[44:47], v[132:135], v[172:175], v[44:47]
	v_mfma_f32_16x16x32_bf16 v[40:43], v[140:143], v[172:175], v[40:43]
	v_mfma_f32_16x16x32_bf16 v[28:31], v[132:135], v[190:193], v[28:31]
	v_mfma_f32_16x16x32_bf16 v[24:27], v[140:143], v[190:193], v[24:27]
	v_mfma_f32_16x16x32_bf16 v[12:15], v[132:135], v[204:207], v[12:15]
	v_mfma_f32_16x16x32_bf16 v[8:11], v[140:143], v[204:207], v[8:11]
	s_setprio 0
	s_setprio 1
	v_mfma_f32_16x16x32_bf16 v[60:63], v[144:147], v[160:163], v[60:63]
	v_mfma_f32_16x16x32_bf16 v[48:51], v[152:155], v[160:163], v[48:51]
	v_mfma_f32_16x16x32_bf16 v[36:39], v[144:147], v[168:171], v[36:39]
	v_mfma_f32_16x16x32_bf16 v[32:35], v[152:155], v[168:171], v[32:35]
	v_mfma_f32_16x16x32_bf16 v[20:23], v[144:147], v[186:189], v[20:23]
	v_mfma_f32_16x16x32_bf16 v[16:19], v[152:155], v[186:189], v[16:19]
	v_mfma_f32_16x16x32_bf16 v[4:7], v[144:147], v[200:203], v[4:7]
	v_mfma_f32_16x16x32_bf16 v[0:3], v[152:155], v[200:203], v[0:3]
	v_mfma_f32_16x16x32_bf16 v[60:63], v[148:151], v[164:167], v[60:63]
	v_mfma_f32_16x16x32_bf16 v[48:51], v[156:159], v[164:167], v[48:51]
	v_mfma_f32_16x16x32_bf16 v[36:39], v[148:151], v[172:175], v[36:39]
	v_mfma_f32_16x16x32_bf16 v[32:35], v[156:159], v[172:175], v[32:35]
	v_mfma_f32_16x16x32_bf16 v[20:23], v[148:151], v[190:193], v[20:23]
	v_mfma_f32_16x16x32_bf16 v[16:19], v[156:159], v[190:193], v[16:19]
	v_mfma_f32_16x16x32_bf16 v[4:7], v[148:151], v[204:207], v[4:7]
	v_mfma_f32_16x16x32_bf16 v[0:3], v[156:159], v[204:207], v[0:3]
	s_setprio 0
	s_barrier
	s_add_i32 s27, 0, 0x18000
	s_add_i32 s44, 0, 0x1c000
	v_add_u32_e32 v140, s27, v212
	v_add_u32_e32 v156, s44, v212
	ds_read_b128 v[128:131], v140
	ds_read_b128 v[132:135], v140 offset:1024
	ds_read_b128 v[136:139], v140 offset:2048
	ds_read_b128 v[140:143], v140 offset:3072
	ds_read_b128 v[144:147], v156
	ds_read_b128 v[148:151], v156 offset:1024
	ds_read_b128 v[152:155], v156 offset:2048
	ds_read_b128 v[156:159], v156 offset:3072
	s_add_u32 s22, s22, 0x40000
	s_addc_u32 s23, s23, 0
	s_mov_b32 m0, s31
	v_lshl_add_u64 v[216:217], s[22:23], 0, v[180:181]
	ds_read_b128 v[160:163], v213 offset:32768
	ds_read_b128 v[164:167], v213 offset:33792
	ds_read_b128 v[168:171], v213 offset:34816
	ds_read_b128 v[172:175], v213 offset:35840
	ds_read_b128 v[186:189], v213 offset:36864
	ds_read_b128 v[190:193], v213 offset:37888
	ds_read_b128 v[200:203], v213 offset:38912
	ds_read_b128 v[204:207], v213 offset:39936
	global_load_lds_dwordx4 v[216:217], off
	v_lshl_add_u64 v[216:217], s[22:23], 0, v[178:179]
	s_mov_b32 m0, s33
	s_nop 0
	global_load_lds_dwordx4 v[216:217], off
	s_waitcnt vmcnt(8)
	s_waitcnt lgkmcnt(0)
	s_barrier
	s_setprio 1
	v_mfma_f32_16x16x32_bf16 v[52:55], v[128:131], v[160:163], v[52:55]
	v_mfma_f32_16x16x32_bf16 v[56:59], v[136:139], v[160:163], v[56:59]
	v_mfma_f32_16x16x32_bf16 v[84:87], v[128:131], v[168:171], v[84:87]
	v_mfma_f32_16x16x32_bf16 v[92:95], v[136:139], v[168:171], v[92:95]
	v_mfma_f32_16x16x32_bf16 v[100:103], v[128:131], v[186:189], v[100:103]
	v_mfma_f32_16x16x32_bf16 v[104:107], v[136:139], v[186:189], v[104:107]
	v_mfma_f32_16x16x32_bf16 v[124:127], v[128:131], v[200:203], v[124:127]
	v_mfma_f32_16x16x32_bf16 v[120:123], v[136:139], v[200:203], v[120:123]
	v_mfma_f32_16x16x32_bf16 v[52:55], v[132:135], v[164:167], v[52:55]
	v_mfma_f32_16x16x32_bf16 v[56:59], v[140:143], v[164:167], v[56:59]
	v_mfma_f32_16x16x32_bf16 v[84:87], v[132:135], v[172:175], v[84:87]
	v_mfma_f32_16x16x32_bf16 v[92:95], v[140:143], v[172:175], v[92:95]
	v_mfma_f32_16x16x32_bf16 v[100:103], v[132:135], v[190:193], v[100:103]
	v_mfma_f32_16x16x32_bf16 v[104:107], v[140:143], v[190:193], v[104:107]
	v_mfma_f32_16x16x32_bf16 v[124:127], v[132:135], v[204:207], v[124:127]
	v_mfma_f32_16x16x32_bf16 v[120:123], v[140:143], v[204:207], v[120:123]
	s_setprio 0
	s_setprio 1
	v_mfma_f32_16x16x32_bf16 v[64:67], v[144:147], v[160:163], v[64:67]
	v_mfma_f32_16x16x32_bf16 v[72:75], v[152:155], v[160:163], v[72:75]
	v_mfma_f32_16x16x32_bf16 v[80:83], v[144:147], v[168:171], v[80:83]
	v_mfma_f32_16x16x32_bf16 v[96:99], v[152:155], v[168:171], v[96:99]
	v_mfma_f32_16x16x32_bf16 v[108:111], v[144:147], v[186:189], v[108:111]
	v_mfma_f32_16x16x32_bf16 v[116:119], v[152:155], v[186:189], v[116:119]
	v_mfma_f32_16x16x32_bf16 v[112:115], v[144:147], v[200:203], v[112:115]
	v_mfma_f32_16x16x32_bf16 v[88:91], v[152:155], v[200:203], v[88:91]
	v_mfma_f32_16x16x32_bf16 v[64:67], v[148:151], v[164:167], v[64:67]
	v_mfma_f32_16x16x32_bf16 v[72:75], v[156:159], v[164:167], v[72:75]
	v_mfma_f32_16x16x32_bf16 v[80:83], v[148:151], v[172:175], v[80:83]
	v_mfma_f32_16x16x32_bf16 v[96:99], v[156:159], v[172:175], v[96:99]
	v_mfma_f32_16x16x32_bf16 v[108:111], v[148:151], v[190:193], v[108:111]
	v_mfma_f32_16x16x32_bf16 v[116:119], v[156:159], v[190:193], v[116:119]
	v_mfma_f32_16x16x32_bf16 v[112:115], v[148:151], v[204:207], v[112:115]
	v_mfma_f32_16x16x32_bf16 v[88:91], v[156:159], v[204:207], v[88:91]
	s_setprio 0
	s_barrier
; #define PG8_STAGE(bufoff, gbase, voff) do { _Pragma("unroll") for (int _i = 0; _i < 2; ++_i) \
;         __builtin_amdgcn_global_load_lds((const unsigned*)((const char*)(gbase) + (voff)[_i]), (LAS unsigned*)(lds + (bufoff) + ldsw + _i * 8192), 16, 0, 0); } while (0)
; #define PG8_LDA(dst, b, h) do { _Pragma("unroll") for (int m = 0; m < 4; ++m) _Pragma("unroll") for (int k = 0; k < 2; ++k) dst[m][k] = *(const LAS bf16x8*)(lds + PG8_SA(b, h) + aoff + m * 2048 + k * 1024); } while (0)
; #define PG8_MMA(ai, bj, At, Bt) do { __builtin_amdgcn_s_setprio(1); _Pragma("unroll") for (int m = 0; m < 4; ++m) _Pragma("unroll") for (int n = 0; n < 2; ++n) _Pragma("unroll") for (int k = 0; k < 2; ++k) \
;         acc[ai][bj][m][n] = __builtin_amdgcn_mfma_f32_16x16x32_bf16(Bt[n][k], At[m][k], acc[ai][bj][m][n], 0, 0, 0); __builtin_amdgcn_s_setprio(0); } while (0)
; #define PG8_WAIT_V(n) asm volatile("s_waitcnt vmcnt(" #n ")" ::: "memory")
; #define PG8_WAIT_L(n) asm volatile("s_waitcnt lgkmcnt(" #n ")" ::: "memory")
; #define PG8_BAR __builtin_amdgcn_s_barrier()
; #define PG8_SCHED __builtin_amdgcn_sched_barrier(0)
; template <class Epi, int N_, int K_, int LDA_>
; __device__ __forceinline__ void gemm_phase(LAS unsigned char* lds, const Gemm g, const Epi& E) {
;     ...
;             PG8_LDA(At, 1, 1); PG8_STAGE(PG8_SB(1, 0), b3, voffB); PG8_STAGE(PG8_SB(1, 1), b3 + hstepB, voffB); PG8_STAGE(PG8_SA(1, 0), a3, voffA);
;             PG8_WAIT_V(8); PG8_WAIT_L(0); PG8_BAR; PG8_MMA(1, 0, At, B0); PG8_MMA(1, 1, At, B1); PG8_BAR; PG8_SCHED;
;         }
;         if (wr == 0) PG8_BAR;
	s_add_i32 s22, s27, s28
	v_lshl_add_u64 v[194:195], v[194:195], 0, s[56:57]
	s_mov_b32 m0, s22
	ds_read_b128 v[160:163], v213 offset:49152
	ds_read_b128 v[164:167], v213 offset:50176
	ds_read_b128 v[168:171], v213 offset:51200
	ds_read_b128 v[172:175], v213 offset:52224
	ds_read_b128 v[186:189], v213 offset:53248
	ds_read_b128 v[190:193], v213 offset:54272
	ds_read_b128 v[200:203], v213 offset:55296
	ds_read_b128 v[204:207], v213 offset:56320
	global_load_lds_dwordx4 v[194:195], off
	s_add_i32 m0, s22, 0x2000
	s_add_u32 s20, s20, 0x40080
	v_lshl_add_u64 v[194:195], v[208:209], 0, s[56:57]
	s_addc_u32 s21, s21, 0
	s_add_i32 s22, s44, s28
	global_load_lds_dwordx4 v[194:195], off
	v_lshl_add_u64 v[194:195], s[20:21], 0, v[196:197]
	s_mov_b32 m0, s22
	s_nop 0
	global_load_lds_dwordx4 v[194:195], off
	v_lshl_add_u64 v[194:195], s[20:21], 0, v[176:177]
	s_add_i32 m0, s22, 0x2000
	s_nop 0
	global_load_lds_dwordx4 v[194:195], off
	v_lshl_add_u64 v[194:195], v[210:211], 0, s[56:57]
	s_mov_b32 m0, s36
	s_nop 0
	global_load_lds_dwordx4 v[194:195], off
	v_lshl_add_u64 v[194:195], v[214:215], 0, s[56:57]
	s_mov_b32 m0, s37
	s_nop 0
	global_load_lds_dwordx4 v[194:195], off
	s_waitcnt vmcnt(8)
	s_waitcnt lgkmcnt(0)
	s_barrier
	s_setprio 1
	v_mfma_f32_16x16x32_bf16 v[76:79], v[128:131], v[160:163], v[76:79]
	v_mfma_f32_16x16x32_bf16 v[68:71], v[136:139], v[160:163], v[68:71]
	v_mfma_f32_16x16x32_bf16 v[44:47], v[128:131], v[168:171], v[44:47]
	v_mfma_f32_16x16x32_bf16 v[40:43], v[136:139], v[168:171], v[40:43]
	v_mfma_f32_16x16x32_bf16 v[28:31], v[128:131], v[186:189], v[28:31]
	v_mfma_f32_16x16x32_bf16 v[24:27], v[136:139], v[186:189], v[24:27]
	v_mfma_f32_16x16x32_bf16 v[12:15], v[128:131], v[200:203], v[12:15]
	v_mfma_f32_16x16x32_bf16 v[8:11], v[136:139], v[200:203], v[8:11]
	v_mfma_f32_16x16x32_bf16 v[76:79], v[132:135], v[164:167], v[76:79]
	v_mfma_f32_16x16x32_bf16 v[68:71], v[140:143], v[164:167], v[68:71]
	v_mfma_f32_16x16x32_bf16 v[44:47], v[132:135], v[172:175], v[44:47]
	v_mfma_f32_16x16x32_bf16 v[40:43], v[140:143], v[172:175], v[40:43]
	v_mfma_f32_16x16x32_bf16 v[28:31], v[132:135], v[190:193], v[28:31]
	v_mfma_f32_16x16x32_bf16 v[24:27], v[140:143], v[190:193], v[24:27]
	v_mfma_f32_16x16x32_bf16 v[12:15], v[132:135], v[204:207], v[12:15]
	v_mfma_f32_16x16x32_bf16 v[8:11], v[140:143], v[204:207], v[8:11]
	s_setprio 0
	s_setprio 1
	v_mfma_f32_16x16x32_bf16 v[60:63], v[144:147], v[160:163], v[60:63]
	v_mfma_f32_16x16x32_bf16 v[48:51], v[152:155], v[160:163], v[48:51]
	v_mfma_f32_16x16x32_bf16 v[36:39], v[144:147], v[168:171], v[36:39]
	v_mfma_f32_16x16x32_bf16 v[32:35], v[152:155], v[168:171], v[32:35]
	v_mfma_f32_16x16x32_bf16 v[20:23], v[144:147], v[186:189], v[20:23]
	v_mfma_f32_16x16x32_bf16 v[16:19], v[152:155], v[186:189], v[16:19]
	v_mfma_f32_16x16x32_bf16 v[4:7], v[144:147], v[200:203], v[4:7]
	v_mfma_f32_16x16x32_bf16 v[0:3], v[152:155], v[200:203], v[0:3]
	v_mfma_f32_16x16x32_bf16 v[60:63], v[148:151], v[164:167], v[60:63]
	v_mfma_f32_16x16x32_bf16 v[48:51], v[156:159], v[164:167], v[48:51]
	v_mfma_f32_16x16x32_bf16 v[36:39], v[148:151], v[172:175], v[36:39]
	v_mfma_f32_16x16x32_bf16 v[32:35], v[156:159], v[172:175], v[32:35]
	v_mfma_f32_16x16x32_bf16 v[20:23], v[148:151], v[190:193], v[20:23]
	v_mfma_f32_16x16x32_bf16 v[16:19], v[156:159], v[190:193], v[16:19]
	v_mfma_f32_16x16x32_bf16 v[4:7], v[148:151], v[204:207], v[4:7]
	v_mfma_f32_16x16x32_bf16 v[0:3], v[156:159], v[204:207], v[0:3]
	s_setprio 0
	s_barrier
	s_add_i32 s26, s26, 2
	s_add_u32 s0, s0, 0x100
	s_addc_u32 s1, s1, 0
	s_add_u32 s24, s24, 0x100
	s_addc_u32 s25, s25, 0
	s_cmp_gt_u32 s26, 13
	s_cbranch_scc0 .LBB0_1069
	s_and_b64 vcc, exec, s[6:7]
	s_cbranch_vccz .LBB0_1072
	s_barrier
